# scan loop rewritten: 2-chunk global prefetch, LDS reads pipelined 2 steps ahead, sa-chain interleaved with y reduction (same arithmetic)
# speedup vs baseline: 1.0136x; 1.0136x over previous
; DI int otid() { int t; asm volatile("v_mov_b32 %0, %1" : "=v"(t) : "v"((int)threadIdx.x)); return t; }
; DI void scan_item(const Params& p, int item, char* smem) {
;   float* sIn = (float*)smem;
;   float* sY = (float*)(smem + 2 * 16 * 6 * 64 * 4);
;   const int tid = otid(), lane = tid & 63, wv = tid >> 6;
;   const int bb = item >> 5, hd = (item >> 3) & 3, dir = (item >> 2) & 1, rg = item & 3;
;   const int rowl = wv * 4 + (lane >> 4), cg4 = (lane & 15) * 4;
;   const u16* SIb = p.SI + ((long)(bb * 4 + hd) * T) * 9 * 64;
;   u16* yb = p.yscan + ((long)dir * MH + (long)bb * T) * 256 + hd * 64 + rg * 16;
;   auto tof = [&](int s) { return dir == 0 ? s : (s < 256 ? 255 - s : 4607 - s); };
;   u32x4 rg_[3];
;   auto gload = [&](int ci) {
; #pragma unroll
;     for (int i = 0; i < 3; i++) {
;       int id = tid + i * 256;
;       int st = id / 48, rem = id % 48, vec = rem >> 3, part = rem & 7;
;       int t = tof(ci * 16 + st);
;       int vi = vec < 3 ? vec : vec + 3 * dir;
;       rg_[i] = *(const u32x4*)(SIb + ((long)t * 9 + vi) * 64 + part * 8);
;     }
;   };
;   auto lstore = [&](int buf) {
; #pragma unroll
;     for (int i = 0; i < 3; i++) {
;       int id = tid + i * 256;
;       int st = id / 48, rem = id % 48, vec = rem >> 3, part = rem & 7;
;       h8 hv = __builtin_bit_cast(h8, rg_[i]);
;       f8 fv = __builtin_convertvector(hv, f8);
;       float* d = sIn + ((buf * 16 + st) * 6 + vec) * 64 + part * 8;
;       *(f32x4v*)d = f32x4v{fv[0], fv[1], fv[2], fv[3]};
;       *(f32x4v*)(d + 4) = f32x4v{fv[4], fv[5], fv[6], fv[7]};
;     }
;   };
;   f32x2 Sa = {0.f, 0.f}, Sb = {0.f, 0.f};
;   __syncthreads();
;   gload(0);
;   lstore(0);
;   __syncthreads();
;   __builtin_amdgcn_s_setprio(3);
;   const int nch = T / 16;
;   const int voff = 128 + rg * 16 + rowl;
;   const int l16 = lane & 15;
.LBB0_396:
	s_ashr_i32 s12, s48, 5
	s_bfe_u32 s21, s48, 0x20003
	s_lshl_b32 s0, s12, 2
	s_or_b32 s0, s0, s21
	s_bfe_u32 s26, s48, 0x10002
	s_mul_hi_i32 s1, s0, 0x4c8000
	s_mul_i32 s0, s0, 0x4c8000
	s_add_u32 s0, s88, s0
	s_addc_u32 s1, s89, s1
	s_mul_i32 s13, s26, 0x4400
	s_mul_hi_i32 s36, s12, 0x1100
	s_mulk_i32 s12, 0x1100
	s_add_u32 s12, s12, s13
	s_addc_u32 s13, s36, 0
	s_lshl_b64 s[12:13], s[12:13], 9
	s_add_u32 s12, s92, s12
	s_addc_u32 s13, s93, s13
	s_lshl_b32 s21, s21, 7
	s_add_u32 s21, s12, s21
	s_addc_u32 s13, s13, 0
	s_lshl_b32 s12, s48, 4
	s_and_b32 s12, s12, 48
	s_lshl_b32 s36, s12, 1
	s_add_u32 s38, s21, s36
	s_mov_b32 s21, 0x2aaaaaab
	v_mov_b32 v24, v198
	s_addc_u32 s39, s13, 0
	v_mul_hi_i32 v0, v24, s21
	v_lshrrev_b32_e32 v1, 31, v0
	v_ashrrev_i32_e32 v0, 3, v0
	s_waitcnt vmcnt(0)
	v_add_u32_e32 v13, v0, v1
	v_mul_lo_u32 v0, v13, 48
	v_sub_u32_e32 v2, v24, v0
	v_ashrrev_i32_e32 v12, 3, v2
	v_lshlrev_b32_e32 v2, 3, v2
	v_and_b32_e32 v38, 56, v2
	v_add_u32_e32 v2, 0x100, v24
	v_mul_hi_i32 v3, v2, s21
	s_movk_i32 s13, 0x2fff
	v_lshrrev_b32_e32 v4, 31, v3
	v_ashrrev_i32_e32 v3, 3, v3
	v_cmp_lt_i32_e32 vcc, s13, v24
	s_mul_i32 s13, s26, 3
	v_add_u32_e32 v17, v3, v4
	v_cndmask_b32_e32 v0, v208, v209, vcc
	v_mov_b32_e32 v8, s13
	v_cmp_lt_i32_e32 vcc, 2, v12
	v_mul_lo_u32 v3, v17, 48
	s_movk_i32 s13, 0x2eff
	v_add_u32_e32 v9, 0x200, v24
	v_cndmask_b32_e32 v1, 0, v8, vcc
	v_sub_u32_e32 v4, v2, v3
	v_cmp_lt_i32_e32 vcc, s13, v24
	v_mul_hi_i32 v10, v9, s21
	s_cmp_eq_u32 s26, 0
	v_ashrrev_i32_e32 v16, 3, v4
	v_cndmask_b32_e32 v2, v208, v209, vcc
	v_lshrrev_b32_e32 v11, 31, v10
	v_ashrrev_i32_e32 v10, 3, v10
	v_sub_u32_e32 v0, v0, v13
	s_cselect_b64 s[36:37], -1, 0
	v_sub_u32_e32 v2, v2, v17
	v_cmp_lt_i32_e32 vcc, 2, v16
	v_add_u32_e32 v21, v10, v11
	v_cndmask_b32_e64 v0, v0, v13, s[36:37]
	v_cndmask_b32_e64 v2, v2, v17, s[36:37]
	v_cndmask_b32_e32 v3, 0, v8, vcc
	v_mul_lo_u32 v10, v21, 48
	v_add_u32_e32 v14, v1, v12
	v_lshl_add_u32 v0, v0, 3, v0
	v_add_u32_e32 v18, v3, v16
	v_lshl_add_u32 v2, v2, 3, v2
	v_sub_u32_e32 v10, v9, v10
	v_ashrrev_i32_e32 v1, 31, v0
	v_ashrrev_i32_e32 v15, 31, v14
	v_ashrrev_i32_e32 v3, 31, v2
	v_ashrrev_i32_e32 v19, 31, v18
	v_ashrrev_i32_e32 v20, 3, v10
	v_lshl_add_u64 v[0:1], v[0:1], 0, v[14:15]
	v_lshl_add_u64 v[2:3], v[18:19], 0, v[2:3]
	v_lshlrev_b32_e32 v4, 3, v4
	v_cmp_lt_i32_e32 vcc, 2, v20
	s_movk_i32 s13, 0x2dff
	v_lshlrev_b64 v[0:1], 7, v[0:1]
	v_lshlrev_b64 v[2:3], 7, v[2:3]
	v_and_b32_e32 v39, 56, v4
	v_cndmask_b32_e32 v8, 0, v8, vcc
	v_cmp_lt_i32_e32 vcc, s13, v24
	v_lshl_add_u64 v[0:1], s[0:1], 0, v[0:1]
	v_lshlrev_b32_e32 v176, 1, v38
	v_lshl_add_u64 v[2:3], s[0:1], 0, v[2:3]
	v_lshlrev_b32_e32 v32, 1, v39
	v_mov_b32_e32 v33, v177
	v_add_u32_e32 v22, v8, v20
	v_cndmask_b32_e32 v8, v208, v209, vcc
	v_lshl_add_u64 v[0:1], v[0:1], 0, v[176:177]
	v_lshl_add_u64 v[4:5], v[2:3], 0, v[32:33]
	v_sub_u32_e32 v8, v8, v21
	s_barrier
	global_load_dwordx4 v[0:3], v[0:1], off
	s_nop 0
	global_load_dwordx4 v[4:7], v[4:5], off
	v_cndmask_b32_e64 v8, v8, v21, s[36:37]
	v_lshl_add_u32 v8, v8, 3, v8
	v_ashrrev_i32_e32 v9, 31, v8
	v_ashrrev_i32_e32 v23, 31, v22
	v_lshl_add_u64 v[8:9], v[22:23], 0, v[8:9]
	v_lshlrev_b32_e32 v10, 3, v10
	v_lshlrev_b64 v[8:9], 7, v[8:9]
	v_and_b32_e32 v43, 56, v10
	v_lshl_add_u64 v[8:9], s[0:1], 0, v[8:9]
	v_lshlrev_b32_e32 v34, 1, v43
	v_mov_b32_e32 v35, v177
	v_lshl_add_u64 v[8:9], v[8:9], 0, v[34:35]
	global_load_dwordx4 v[8:11], v[8:9], off
	v_ashrrev_i32_e32 v25, 4, v24
	v_lshrrev_b32_e32 v26, 4, v24
	v_bfi_b32 v42, -4, v25, v26
	v_and_b32_e32 v36, 15, v24
	v_mad_u64_u32 v[40:41], s[40:41], v13, 6, v[12:13]
	v_lshlrev_b32_e32 v38, 2, v38
	v_lshl_or_b32 v40, v40, 8, v38
	v_lshlrev_b32_e32 v39, 2, v39
	v_mad_u64_u32 v[44:45], s[40:41], v21, 6, v[20:21]
	s_mov_b32 s73, s69
	v_lshlrev_b32_e32 v37, 2, v36
	s_mov_b32 s26, 0
	s_waitcnt vmcnt(2)
	v_cvt_f32_f16_e32 v30, v1
	v_cvt_f32_f16_e32 v28, v0
	v_cvt_f32_f16_sdwa v31, v1 dst_sel:DWORD dst_unused:UNUSED_PAD src0_sel:WORD_1
	v_cvt_f32_f16_sdwa v29, v0 dst_sel:DWORD dst_unused:UNUSED_PAD src0_sel:WORD_1
	v_cvt_f32_f16_e32 v26, v3
	v_cvt_f32_f16_e32 v24, v2
	v_cvt_f32_f16_sdwa v27, v3 dst_sel:DWORD dst_unused:UNUSED_PAD src0_sel:WORD_1
	v_cvt_f32_f16_sdwa v25, v2 dst_sel:DWORD dst_unused:UNUSED_PAD src0_sel:WORD_1
	ds_write_b128 v40, v[28:31]
	ds_write_b128 v40, v[24:27] offset:16
	s_waitcnt vmcnt(1)
	v_cvt_f32_f16_e32 v30, v5
	v_cvt_f32_f16_e32 v28, v4
	v_cvt_f32_f16_sdwa v31, v5 dst_sel:DWORD dst_unused:UNUSED_PAD src0_sel:WORD_1
	v_cvt_f32_f16_sdwa v29, v4 dst_sel:DWORD dst_unused:UNUSED_PAD src0_sel:WORD_1
	v_cvt_f32_f16_e32 v26, v7
	v_cvt_f32_f16_e32 v24, v6
	v_cvt_f32_f16_sdwa v27, v7 dst_sel:DWORD dst_unused:UNUSED_PAD src0_sel:WORD_1
	v_cvt_f32_f16_sdwa v25, v6 dst_sel:DWORD dst_unused:UNUSED_PAD src0_sel:WORD_1
	v_mad_u64_u32 v[40:41], s[40:41], v17, 6, v[16:17]
	v_lshl_or_b32 v40, v40, 8, v39
	ds_write_b128 v40, v[28:31]
	ds_write_b128 v40, v[24:27] offset:16
	s_waitcnt vmcnt(0)
	v_cvt_f32_f16_e32 v26, v11
	v_cvt_f32_f16_e32 v24, v10
	v_cvt_f32_f16_sdwa v27, v11 dst_sel:DWORD dst_unused:UNUSED_PAD src0_sel:WORD_1
	v_cvt_f32_f16_sdwa v25, v10 dst_sel:DWORD dst_unused:UNUSED_PAD src0_sel:WORD_1
	v_cvt_f32_f16_e32 v30, v9
	v_cvt_f32_f16_e32 v28, v8
	v_cvt_f32_f16_sdwa v31, v9 dst_sel:DWORD dst_unused:UNUSED_PAD src0_sel:WORD_1
	v_cvt_f32_f16_sdwa v29, v8 dst_sel:DWORD dst_unused:UNUSED_PAD src0_sel:WORD_1
	v_lshlrev_b32_e32 v40, 2, v43
	v_lshl_or_b32 v41, v44, 8, v40
	ds_write_b128 v41, v[28:31]
	ds_write_b128 v41, v[24:27] offset:16
	s_waitcnt lgkmcnt(0)
	s_barrier
	s_setprio 3
	v_lshl_add_u64 v[26:27], s[0:1], 0, v[32:33]
	v_ashrrev_i32_e32 v43, 31, v42
	v_mov_b32_e32 v32, 0
	v_lshl_add_u64 v[24:25], s[0:1], 0, v[176:177]
	v_lshl_add_u64 v[28:29], s[0:1], 0, v[34:35]
	v_lshl_add_u64 v[30:31], v[42:43], 1, s[38:39]
	v_cmp_eq_u32_e64 s[38:39], 0, v36
	v_cmp_eq_u32_e64 s[40:41], 1, v36
	v_cmp_eq_u32_e64 s[42:43], 2, v36
	v_cmp_eq_u32_e64 s[44:45], 3, v36
	v_cmp_eq_u32_e64 s[46:47], 4, v36
	v_cmp_eq_u32_e64 s[48:49], 5, v36
	v_cmp_eq_u32_e64 s[50:51], 6, v36
	v_cmp_eq_u32_e64 s[52:53], 7, v36
	v_cmp_eq_u32_e64 s[54:55], 8, v36
	v_cmp_eq_u32_e64 s[56:57], 9, v36
	v_cmp_eq_u32_e64 s[58:59], 10, v36
	v_cmp_eq_u32_e64 s[60:61], 11, v36
	v_cmp_eq_u32_e64 s[62:63], 12, v36
	v_cmp_eq_u32_e64 s[64:65], 13, v36
	v_cmp_eq_u32_e64 s[66:67], 14, v36
	v_cmp_eq_u32_e64 s[68:69], 15, v36
	v_add_u32_e32 v41, s12, v42
	v_sub_u32_e32 v42, 0, v36
	v_add_u32_e32 v43, 16, v21
	v_sub_u32_e32 v44, -16, v21
	v_add_u32_e32 v45, 16, v17
	v_sub_u32_e32 v46, -16, v17
	v_add_u32_e32 v47, 16, v13
	v_sub_u32_e32 v48, -16, v13
	s_mov_b32 s21, 0
	v_mov_b32_e32 v90, v32
	v_mov_b32_e32 v91, v32
	v_mov_b32_e32 v92, v32
	v_mov_b32_e32 v93, v32
	s_branch .LBB0_398
; DI void scan_item(const Params& p, int item, char* smem) {
;     ...
;   auto gload = [&](int ci) {
; #pragma unroll
;     for (int i = 0; i < 3; i++) {
;       int id = tid + i * 256;
;       int st = id / 48, rem = id % 48, vec = rem >> 3, part = rem & 7;
;       int t = tof(ci * 16 + st);
;       int vi = vec < 3 ? vec : vec + 3 * dir;
;       rg_[i] = *(const u32x4*)(SIb + ((long)t * 9 + vi) * 64 + part * 8);
;     }
;   };
;     ...
;   auto ldstep = [&](const float* b) {
;     StepIn x;
;     x.r = *(const f32x4v*)(b + cg4); x.k = *(const f32x4v*)(b + 64 + cg4); x.v = b[voff];
;     x.w = *(const f32x4v*)(b + 192 + cg4); x.d = *(const f32x4v*)(b + 256 + cg4); x.b = *(const f32x4v*)(b + 320 + cg4);
;     return x;
;   };
;   for (int ci = 0; ci < nch; ci++) {
;     if (ci + 1 < nch) gload(ci + 1);
;     const float* base = sIn + (ci & 1) * 16 * 6 * 64;
;     float ykeep = 0.f;
;     StepIn cur = ldstep(base);
; #pragma unroll
;     for (int st = 0; st < 16; st++) {
;       StepIn nxt = cur;
;       if (st + 1 < 16) nxt = ldstep(base + (st + 1) * 6 * 64);
;       __builtin_amdgcn_sched_barrier(0);
;       f32x2 ra = {cur.r.x, cur.r.y}, rb = {cur.r.z, cur.r.w}, ka = {cur.k.x, cur.k.y}, kb = {cur.k.z, cur.k.w};
;       f32x2 wa = {cur.w.x, cur.w.y}, wb = {cur.w.z, cur.w.w}, da = {cur.d.x, cur.d.y}, db = {cur.d.z, cur.d.w};
;       f32x2 ba = {cur.b.x, cur.b.y}, bb2 = {cur.b.z, cur.b.w};
;       f32x2 pp = Sa * ka + Sb * kb;
;       float sa = allreduce16(pp.x + pp.y);
;       f32x2 vv2 = {cur.v, cur.v};
;       f32x2 sa2 = {sa, sa};
;       Sa = (Sa * wa + vv2 * da) - sa2 * ba;
;       Sb = (Sb * wb + vv2 * db) - sa2 * bb2;
;       f32x2 yy = Sa * ra + Sb * rb;
;       float y = allreduce16(yy.x + yy.y);
;       ykeep = (l16 == st) ? y : ykeep;
.LBB0_398:
	v_lshlrev_b32_e32 v49, 2, v37
	v_lshlrev_b32_e32 v50, 2, v41
	v_mad_u32_u24 v32, v13, 6, v12
	v_mad_u32_u24 v33, v17, 6, v16
	v_mad_u32_u24 v34, v21, 6, v20
	v_lshl_or_b32 v32, v32, 8, v38
	v_lshl_or_b32 v33, v33, 8, v39
	v_lshl_or_b32 v34, v34, 8, v40
	s_movk_i32 s72, 0x10
	v_add_u32_e32 v0, s72, v13
	v_add_u32_e32 v4, s72, v17
	v_add_u32_e32 v8, s72, v21
	v_cmp_lt_i32_e32 vcc, 0xff, v0
	s_nop 1
	v_cndmask_b32_e32 v1, v208, v209, vcc
	v_cmp_lt_i32_e32 vcc, 0xff, v4
	v_sub_u32_e32 v1, v1, v0
	v_cndmask_b32_e64 v0, v1, v0, s[36:37]
	v_cndmask_b32_e32 v5, v208, v209, vcc
	v_cmp_lt_i32_e32 vcc, 0xff, v8
	v_sub_u32_e32 v5, v5, v4
	v_cndmask_b32_e64 v4, v5, v4, s[36:37]
	v_cndmask_b32_e32 v9, v208, v209, vcc
	v_sub_u32_e32 v9, v9, v8
	v_cndmask_b32_e64 v8, v9, v8, s[36:37]
	v_mad_i64_i32 v[0:1], s[12:13], v0, 9, v[14:15]
	v_mad_i64_i32 v[4:5], s[12:13], v4, 9, v[18:19]
	v_mad_i64_i32 v[8:9], s[12:13], v8, 9, v[22:23]
	v_lshlrev_b64 v[0:1], 7, v[0:1]
	v_lshlrev_b64 v[4:5], 7, v[4:5]
	v_lshlrev_b64 v[8:9], 7, v[8:9]
	v_lshl_add_u64 v[0:1], v[24:25], 0, v[0:1]
	v_lshl_add_u64 v[4:5], v[26:27], 0, v[4:5]
	v_lshl_add_u64 v[8:9], v[28:29], 0, v[8:9]
	global_load_dwordx4 v[0:3], v[0:1], off
	global_load_dwordx4 v[4:7], v[4:5], off
	global_load_dwordx4 v[8:11], v[8:9], off
	s_mov_b32 s26, 0
.Lscan_loop:
	ds_read_b128 v[72:75], v49 offset:256
	ds_read_b32 v88, v50 offset:512
	ds_read_b128 v[80:83], v49 offset:1024
	ds_read_b128 v[76:79], v49 offset:768
	ds_read_b128 v[84:87], v49 offset:1280
	ds_read_b128 v[68:71], v49
	ds_read_b128 v[100:103], v49 offset:1792
	ds_read_b32 v116, v50 offset:2048
	ds_read_b128 v[108:111], v49 offset:2560
	ds_read_b128 v[104:107], v49 offset:2304
	ds_read_b128 v[112:115], v49 offset:2816
	ds_read_b128 v[96:99], v49 offset:1536
	s_add_i32 s72, s26, 32
	s_min_u32 s72, s72, 0x10f0
	v_add_u32_e32 v162, s72, v13
	v_add_u32_e32 v166, s72, v17
	v_add_u32_e32 v170, s72, v21
	v_cmp_lt_i32_e32 vcc, 0xff, v162
	s_nop 1
	v_cndmask_b32_e32 v163, v208, v209, vcc
	v_cmp_lt_i32_e32 vcc, 0xff, v166
	v_sub_u32_e32 v163, v163, v162
	v_cndmask_b32_e64 v162, v163, v162, s[36:37]
	v_cndmask_b32_e32 v167, v208, v209, vcc
	v_cmp_lt_i32_e32 vcc, 0xff, v170
	v_sub_u32_e32 v167, v167, v166
	v_cndmask_b32_e64 v166, v167, v166, s[36:37]
	v_cndmask_b32_e32 v171, v208, v209, vcc
	v_sub_u32_e32 v171, v171, v170
	v_cndmask_b32_e64 v170, v171, v170, s[36:37]
	v_mad_i64_i32 v[162:163], s[12:13], v162, 9, v[14:15]
	v_mad_i64_i32 v[166:167], s[12:13], v166, 9, v[18:19]
	v_mad_i64_i32 v[170:171], s[12:13], v170, 9, v[22:23]
	v_lshlrev_b64 v[162:163], 7, v[162:163]
	v_lshlrev_b64 v[166:167], 7, v[166:167]
	v_lshlrev_b64 v[170:171], 7, v[170:171]
	v_lshl_add_u64 v[162:163], v[24:25], 0, v[162:163]
	v_lshl_add_u64 v[166:167], v[26:27], 0, v[166:167]
	v_lshl_add_u64 v[170:171], v[28:29], 0, v[170:171]
	global_load_dwordx4 v[162:165], v[162:163], off
	global_load_dwordx4 v[166:169], v[166:167], off
	global_load_dwordx4 v[170:173], v[170:171], off
	s_waitcnt lgkmcnt(6)
	ds_read_b128 v[122:125], v49 offset:3328
	ds_read_b32 v138, v50 offset:3584
	ds_read_b128 v[130:133], v49 offset:4096
	ds_read_b128 v[126:129], v49 offset:3840
	ds_read_b128 v[134:137], v49 offset:4352
	ds_read_b128 v[118:121], v49 offset:3072
	v_pk_mul_f32 v[56:57], v[90:91], v[72:73]
	v_pk_mul_f32 v[60:61], v[88:89], v[80:81] op_sel_hi:[0,1]
	v_pk_fma_f32 v[56:57], v[92:93], v[74:75], v[56:57]
	v_pk_mul_f32 v[62:63], v[88:89], v[82:83] op_sel_hi:[0,1]
	v_add_f32_e32 v58, v56, v57
	v_pk_fma_f32 v[60:61], v[90:91], v[76:77], v[60:61]
	v_pk_fma_f32 v[62:63], v[92:93], v[78:79], v[62:63]
	v_add_f32_dpp v58, v58, v58 quad_perm:[1,0,3,2] row_mask:0xf bank_mask:0xf bound_ctrl:1
	s_nop 1
	v_add_f32_dpp v58, v58, v58 quad_perm:[2,3,0,1] row_mask:0xf bank_mask:0xf bound_ctrl:1
	s_nop 1
	v_add_f32_dpp v58, v58, v58 row_half_mirror row_mask:0xf bank_mask:0xf bound_ctrl:1
	s_nop 1
	v_add_f32_dpp v58, v58, v58 row_mirror row_mask:0xf bank_mask:0xf bound_ctrl:1
	s_nop 0
	v_pk_fma_f32 v[90:91], v[84:85], v[58:59], v[60:61] op_sel_hi:[1,0,1] neg_lo:[1,0,0] neg_hi:[1,0,0]
	v_pk_fma_f32 v[92:93], v[86:87], v[58:59], v[62:63] op_sel_hi:[1,0,1] neg_lo:[1,0,0] neg_hi:[1,0,0]
	s_waitcnt lgkmcnt(6)
	ds_read_b128 v[144:147], v49 offset:4864
	ds_read_b32 v160, v50 offset:5120
	ds_read_b128 v[152:155], v49 offset:5632
	ds_read_b128 v[148:151], v49 offset:5376
	ds_read_b128 v[156:159], v49 offset:5888
	ds_read_b128 v[140:143], v49 offset:4608
	v_pk_mul_f32 v[56:57], v[90:91], v[100:101]
	v_pk_mul_f32 v[64:65], v[70:71], v[92:93]
	v_pk_fma_f32 v[56:57], v[92:93], v[102:103], v[56:57]
	v_pk_fma_f32 v[64:65], v[68:69], v[90:91], v[64:65]
	v_add_f32_e32 v58, v56, v57
	v_add_f32_e32 v66, v64, v65
	v_pk_mul_f32 v[60:61], v[116:117], v[108:109] op_sel_hi:[0,1]
	v_add_f32_dpp v58, v58, v58 quad_perm:[1,0,3,2] row_mask:0xf bank_mask:0xf bound_ctrl:1
	v_add_f32_dpp v66, v66, v66 quad_perm:[1,0,3,2] row_mask:0xf bank_mask:0xf bound_ctrl:1
	v_pk_fma_f32 v[60:61], v[90:91], v[104:105], v[60:61]
	v_add_f32_dpp v58, v58, v58 quad_perm:[2,3,0,1] row_mask:0xf bank_mask:0xf bound_ctrl:1
	v_add_f32_dpp v66, v66, v66 quad_perm:[2,3,0,1] row_mask:0xf bank_mask:0xf bound_ctrl:1
	v_pk_mul_f32 v[62:63], v[116:117], v[110:111] op_sel_hi:[0,1]
	v_add_f32_dpp v58, v58, v58 row_half_mirror row_mask:0xf bank_mask:0xf bound_ctrl:1
	v_add_f32_dpp v66, v66, v66 row_half_mirror row_mask:0xf bank_mask:0xf bound_ctrl:1
	v_pk_fma_f32 v[62:63], v[92:93], v[106:107], v[62:63]
	v_add_f32_dpp v58, v58, v58 row_mirror row_mask:0xf bank_mask:0xf bound_ctrl:1
	v_add_f32_dpp v66, v66, v66 row_mirror row_mask:0xf bank_mask:0xf bound_ctrl:1
	v_pk_fma_f32 v[90:91], v[112:113], v[58:59], v[60:61] op_sel_hi:[1,0,1] neg_lo:[1,0,0] neg_hi:[1,0,0]
	v_pk_fma_f32 v[92:93], v[114:115], v[58:59], v[62:63] op_sel_hi:[1,0,1] neg_lo:[1,0,0] neg_hi:[1,0,0]
	v_cndmask_b32_e64 v67, 0, v66, s[38:39]
	s_waitcnt lgkmcnt(6)
; DI void scan_item(const Params& p, int item, char* smem) {
;     ...
;     for (int st = 0; st < 16; st++) {
;       StepIn nxt = cur;
;       if (st + 1 < 16) nxt = ldstep(base + (st + 1) * 6 * 64);
;       __builtin_amdgcn_sched_barrier(0);
;       f32x2 ra = {cur.r.x, cur.r.y}, rb = {cur.r.z, cur.r.w}, ka = {cur.k.x, cur.k.y}, kb = {cur.k.z, cur.k.w};
;       f32x2 wa = {cur.w.x, cur.w.y}, wb = {cur.w.z, cur.w.w}, da = {cur.d.x, cur.d.y}, db = {cur.d.z, cur.d.w};
;       f32x2 ba = {cur.b.x, cur.b.y}, bb2 = {cur.b.z, cur.b.w};
;       f32x2 pp = Sa * ka + Sb * kb;
;       float sa = allreduce16(pp.x + pp.y);
;       f32x2 vv2 = {cur.v, cur.v};
;       f32x2 sa2 = {sa, sa};
;       Sa = (Sa * wa + vv2 * da) - sa2 * ba;
;       Sb = (Sb * wb + vv2 * db) - sa2 * bb2;
;       f32x2 yy = Sa * ra + Sb * rb;
;       float y = allreduce16(yy.x + yy.y);
;       ykeep = (l16 == st) ? y : ykeep;
;       cur = nxt;
	ds_read_b128 v[72:75], v49 offset:6400
	ds_read_b32 v88, v50 offset:6656
	ds_read_b128 v[80:83], v49 offset:7168
	ds_read_b128 v[76:79], v49 offset:6912
	ds_read_b128 v[84:87], v49 offset:7424
	ds_read_b128 v[68:71], v49 offset:6144
	v_pk_mul_f32 v[56:57], v[90:91], v[122:123]
	v_pk_mul_f32 v[64:65], v[98:99], v[92:93]
	v_pk_fma_f32 v[56:57], v[92:93], v[124:125], v[56:57]
	v_pk_fma_f32 v[64:65], v[96:97], v[90:91], v[64:65]
	v_add_f32_e32 v58, v56, v57
	v_add_f32_e32 v66, v64, v65
	v_pk_mul_f32 v[60:61], v[138:139], v[130:131] op_sel_hi:[0,1]
	v_add_f32_dpp v58, v58, v58 quad_perm:[1,0,3,2] row_mask:0xf bank_mask:0xf bound_ctrl:1
	v_add_f32_dpp v66, v66, v66 quad_perm:[1,0,3,2] row_mask:0xf bank_mask:0xf bound_ctrl:1
	v_pk_fma_f32 v[60:61], v[90:91], v[126:127], v[60:61]
	v_add_f32_dpp v58, v58, v58 quad_perm:[2,3,0,1] row_mask:0xf bank_mask:0xf bound_ctrl:1
	v_add_f32_dpp v66, v66, v66 quad_perm:[2,3,0,1] row_mask:0xf bank_mask:0xf bound_ctrl:1
	v_pk_mul_f32 v[62:63], v[138:139], v[132:133] op_sel_hi:[0,1]
	v_add_f32_dpp v58, v58, v58 row_half_mirror row_mask:0xf bank_mask:0xf bound_ctrl:1
	v_add_f32_dpp v66, v66, v66 row_half_mirror row_mask:0xf bank_mask:0xf bound_ctrl:1
	v_pk_fma_f32 v[62:63], v[92:93], v[128:129], v[62:63]
	v_add_f32_dpp v58, v58, v58 row_mirror row_mask:0xf bank_mask:0xf bound_ctrl:1
	v_add_f32_dpp v66, v66, v66 row_mirror row_mask:0xf bank_mask:0xf bound_ctrl:1
	v_pk_fma_f32 v[90:91], v[134:135], v[58:59], v[60:61] op_sel_hi:[1,0,1] neg_lo:[1,0,0] neg_hi:[1,0,0]
	v_pk_fma_f32 v[92:93], v[136:137], v[58:59], v[62:63] op_sel_hi:[1,0,1] neg_lo:[1,0,0] neg_hi:[1,0,0]
	v_cndmask_b32_e64 v67, v67, v66, s[40:41]
	s_waitcnt lgkmcnt(6)
	ds_read_b128 v[100:103], v49 offset:7936
	ds_read_b32 v116, v50 offset:8192
	ds_read_b128 v[108:111], v49 offset:8704
	ds_read_b128 v[104:107], v49 offset:8448
	ds_read_b128 v[112:115], v49 offset:8960
	ds_read_b128 v[96:99], v49 offset:7680
	v_pk_mul_f32 v[56:57], v[90:91], v[144:145]
	v_pk_mul_f32 v[64:65], v[120:121], v[92:93]
	v_pk_fma_f32 v[56:57], v[92:93], v[146:147], v[56:57]
	v_pk_fma_f32 v[64:65], v[118:119], v[90:91], v[64:65]
	v_add_f32_e32 v58, v56, v57
	v_add_f32_e32 v66, v64, v65
	v_pk_mul_f32 v[60:61], v[160:161], v[152:153] op_sel_hi:[0,1]
	v_add_f32_dpp v58, v58, v58 quad_perm:[1,0,3,2] row_mask:0xf bank_mask:0xf bound_ctrl:1
	v_add_f32_dpp v66, v66, v66 quad_perm:[1,0,3,2] row_mask:0xf bank_mask:0xf bound_ctrl:1
	v_pk_fma_f32 v[60:61], v[90:91], v[148:149], v[60:61]
	v_add_f32_dpp v58, v58, v58 quad_perm:[2,3,0,1] row_mask:0xf bank_mask:0xf bound_ctrl:1
	v_add_f32_dpp v66, v66, v66 quad_perm:[2,3,0,1] row_mask:0xf bank_mask:0xf bound_ctrl:1
	v_pk_mul_f32 v[62:63], v[160:161], v[154:155] op_sel_hi:[0,1]
	v_add_f32_dpp v58, v58, v58 row_half_mirror row_mask:0xf bank_mask:0xf bound_ctrl:1
	v_add_f32_dpp v66, v66, v66 row_half_mirror row_mask:0xf bank_mask:0xf bound_ctrl:1
	v_pk_fma_f32 v[62:63], v[92:93], v[150:151], v[62:63]
	v_add_f32_dpp v58, v58, v58 row_mirror row_mask:0xf bank_mask:0xf bound_ctrl:1
	v_add_f32_dpp v66, v66, v66 row_mirror row_mask:0xf bank_mask:0xf bound_ctrl:1
	v_pk_fma_f32 v[90:91], v[156:157], v[58:59], v[60:61] op_sel_hi:[1,0,1] neg_lo:[1,0,0] neg_hi:[1,0,0]
	v_pk_fma_f32 v[92:93], v[158:159], v[58:59], v[62:63] op_sel_hi:[1,0,1] neg_lo:[1,0,0] neg_hi:[1,0,0]
	v_cndmask_b32_e64 v67, v67, v66, s[42:43]
	s_waitcnt lgkmcnt(6)
	ds_read_b128 v[122:125], v49 offset:9472
	ds_read_b32 v138, v50 offset:9728
	ds_read_b128 v[130:133], v49 offset:10240
	ds_read_b128 v[126:129], v49 offset:9984
	ds_read_b128 v[134:137], v49 offset:10496
	ds_read_b128 v[118:121], v49 offset:9216
	v_pk_mul_f32 v[56:57], v[90:91], v[72:73]
	v_pk_mul_f32 v[64:65], v[142:143], v[92:93]
	v_pk_fma_f32 v[56:57], v[92:93], v[74:75], v[56:57]
	v_pk_fma_f32 v[64:65], v[140:141], v[90:91], v[64:65]
	v_add_f32_e32 v58, v56, v57
	v_add_f32_e32 v66, v64, v65
	v_pk_mul_f32 v[60:61], v[88:89], v[80:81] op_sel_hi:[0,1]
	v_add_f32_dpp v58, v58, v58 quad_perm:[1,0,3,2] row_mask:0xf bank_mask:0xf bound_ctrl:1
	v_add_f32_dpp v66, v66, v66 quad_perm:[1,0,3,2] row_mask:0xf bank_mask:0xf bound_ctrl:1
	v_pk_fma_f32 v[60:61], v[90:91], v[76:77], v[60:61]
	v_add_f32_dpp v58, v58, v58 quad_perm:[2,3,0,1] row_mask:0xf bank_mask:0xf bound_ctrl:1
	v_add_f32_dpp v66, v66, v66 quad_perm:[2,3,0,1] row_mask:0xf bank_mask:0xf bound_ctrl:1
	v_pk_mul_f32 v[62:63], v[88:89], v[82:83] op_sel_hi:[0,1]
	v_add_f32_dpp v58, v58, v58 row_half_mirror row_mask:0xf bank_mask:0xf bound_ctrl:1
	v_add_f32_dpp v66, v66, v66 row_half_mirror row_mask:0xf bank_mask:0xf bound_ctrl:1
	v_pk_fma_f32 v[62:63], v[92:93], v[78:79], v[62:63]
	v_add_f32_dpp v58, v58, v58 row_mirror row_mask:0xf bank_mask:0xf bound_ctrl:1
	v_add_f32_dpp v66, v66, v66 row_mirror row_mask:0xf bank_mask:0xf bound_ctrl:1
	v_pk_fma_f32 v[90:91], v[84:85], v[58:59], v[60:61] op_sel_hi:[1,0,1] neg_lo:[1,0,0] neg_hi:[1,0,0]
	v_pk_fma_f32 v[92:93], v[86:87], v[58:59], v[62:63] op_sel_hi:[1,0,1] neg_lo:[1,0,0] neg_hi:[1,0,0]
	v_cndmask_b32_e64 v67, v67, v66, s[44:45]
	s_waitcnt lgkmcnt(6)
; DI void scan_item(const Params& p, int item, char* smem) {
;     ...
;     for (int st = 0; st < 16; st++) {
;       StepIn nxt = cur;
;       if (st + 1 < 16) nxt = ldstep(base + (st + 1) * 6 * 64);
;       __builtin_amdgcn_sched_barrier(0);
;       f32x2 ra = {cur.r.x, cur.r.y}, rb = {cur.r.z, cur.r.w}, ka = {cur.k.x, cur.k.y}, kb = {cur.k.z, cur.k.w};
;       f32x2 wa = {cur.w.x, cur.w.y}, wb = {cur.w.z, cur.w.w}, da = {cur.d.x, cur.d.y}, db = {cur.d.z, cur.d.w};
;       f32x2 ba = {cur.b.x, cur.b.y}, bb2 = {cur.b.z, cur.b.w};
;       f32x2 pp = Sa * ka + Sb * kb;
;       float sa = allreduce16(pp.x + pp.y);
;       f32x2 vv2 = {cur.v, cur.v};
;       f32x2 sa2 = {sa, sa};
;       Sa = (Sa * wa + vv2 * da) - sa2 * ba;
;       Sb = (Sb * wb + vv2 * db) - sa2 * bb2;
;       f32x2 yy = Sa * ra + Sb * rb;
;       float y = allreduce16(yy.x + yy.y);
;       ykeep = (l16 == st) ? y : ykeep;
;       cur = nxt;
	ds_read_b128 v[144:147], v49 offset:11008
	ds_read_b32 v160, v50 offset:11264
	ds_read_b128 v[152:155], v49 offset:11776
	ds_read_b128 v[148:151], v49 offset:11520
	ds_read_b128 v[156:159], v49 offset:12032
	ds_read_b128 v[140:143], v49 offset:10752
	v_pk_mul_f32 v[56:57], v[90:91], v[100:101]
	v_pk_mul_f32 v[64:65], v[70:71], v[92:93]
	v_pk_fma_f32 v[56:57], v[92:93], v[102:103], v[56:57]
	v_pk_fma_f32 v[64:65], v[68:69], v[90:91], v[64:65]
	v_add_f32_e32 v58, v56, v57
	v_add_f32_e32 v66, v64, v65
	v_pk_mul_f32 v[60:61], v[116:117], v[108:109] op_sel_hi:[0,1]
	v_add_f32_dpp v58, v58, v58 quad_perm:[1,0,3,2] row_mask:0xf bank_mask:0xf bound_ctrl:1
	v_add_f32_dpp v66, v66, v66 quad_perm:[1,0,3,2] row_mask:0xf bank_mask:0xf bound_ctrl:1
	v_pk_fma_f32 v[60:61], v[90:91], v[104:105], v[60:61]
	v_add_f32_dpp v58, v58, v58 quad_perm:[2,3,0,1] row_mask:0xf bank_mask:0xf bound_ctrl:1
	v_add_f32_dpp v66, v66, v66 quad_perm:[2,3,0,1] row_mask:0xf bank_mask:0xf bound_ctrl:1
	v_pk_mul_f32 v[62:63], v[116:117], v[110:111] op_sel_hi:[0,1]
	v_add_f32_dpp v58, v58, v58 row_half_mirror row_mask:0xf bank_mask:0xf bound_ctrl:1
	v_add_f32_dpp v66, v66, v66 row_half_mirror row_mask:0xf bank_mask:0xf bound_ctrl:1
	v_pk_fma_f32 v[62:63], v[92:93], v[106:107], v[62:63]
	v_add_f32_dpp v58, v58, v58 row_mirror row_mask:0xf bank_mask:0xf bound_ctrl:1
	v_add_f32_dpp v66, v66, v66 row_mirror row_mask:0xf bank_mask:0xf bound_ctrl:1
	v_pk_fma_f32 v[90:91], v[112:113], v[58:59], v[60:61] op_sel_hi:[1,0,1] neg_lo:[1,0,0] neg_hi:[1,0,0]
	v_pk_fma_f32 v[92:93], v[114:115], v[58:59], v[62:63] op_sel_hi:[1,0,1] neg_lo:[1,0,0] neg_hi:[1,0,0]
	v_cndmask_b32_e64 v67, v67, v66, s[46:47]
	s_waitcnt lgkmcnt(6)
	ds_read_b128 v[72:75], v49 offset:12544
	ds_read_b32 v88, v50 offset:12800
	ds_read_b128 v[80:83], v49 offset:13312
	ds_read_b128 v[76:79], v49 offset:13056
	ds_read_b128 v[84:87], v49 offset:13568
	ds_read_b128 v[68:71], v49 offset:12288
	v_pk_mul_f32 v[56:57], v[90:91], v[122:123]
	v_pk_mul_f32 v[64:65], v[98:99], v[92:93]
	v_pk_fma_f32 v[56:57], v[92:93], v[124:125], v[56:57]
	v_pk_fma_f32 v[64:65], v[96:97], v[90:91], v[64:65]
	v_add_f32_e32 v58, v56, v57
	v_add_f32_e32 v66, v64, v65
	v_pk_mul_f32 v[60:61], v[138:139], v[130:131] op_sel_hi:[0,1]
	v_add_f32_dpp v58, v58, v58 quad_perm:[1,0,3,2] row_mask:0xf bank_mask:0xf bound_ctrl:1
	v_add_f32_dpp v66, v66, v66 quad_perm:[1,0,3,2] row_mask:0xf bank_mask:0xf bound_ctrl:1
	v_pk_fma_f32 v[60:61], v[90:91], v[126:127], v[60:61]
	v_add_f32_dpp v58, v58, v58 quad_perm:[2,3,0,1] row_mask:0xf bank_mask:0xf bound_ctrl:1
	v_add_f32_dpp v66, v66, v66 quad_perm:[2,3,0,1] row_mask:0xf bank_mask:0xf bound_ctrl:1
	v_pk_mul_f32 v[62:63], v[138:139], v[132:133] op_sel_hi:[0,1]
	v_add_f32_dpp v58, v58, v58 row_half_mirror row_mask:0xf bank_mask:0xf bound_ctrl:1
	v_add_f32_dpp v66, v66, v66 row_half_mirror row_mask:0xf bank_mask:0xf bound_ctrl:1
	v_pk_fma_f32 v[62:63], v[92:93], v[128:129], v[62:63]
	v_add_f32_dpp v58, v58, v58 row_mirror row_mask:0xf bank_mask:0xf bound_ctrl:1
	v_add_f32_dpp v66, v66, v66 row_mirror row_mask:0xf bank_mask:0xf bound_ctrl:1
	v_pk_fma_f32 v[90:91], v[134:135], v[58:59], v[60:61] op_sel_hi:[1,0,1] neg_lo:[1,0,0] neg_hi:[1,0,0]
	v_pk_fma_f32 v[92:93], v[136:137], v[58:59], v[62:63] op_sel_hi:[1,0,1] neg_lo:[1,0,0] neg_hi:[1,0,0]
	v_cndmask_b32_e64 v67, v67, v66, s[48:49]
	s_waitcnt lgkmcnt(6)
	ds_read_b128 v[100:103], v49 offset:14080
	ds_read_b32 v116, v50 offset:14336
	ds_read_b128 v[108:111], v49 offset:14848
	ds_read_b128 v[104:107], v49 offset:14592
	ds_read_b128 v[112:115], v49 offset:15104
	ds_read_b128 v[96:99], v49 offset:13824
	v_pk_mul_f32 v[56:57], v[90:91], v[144:145]
	v_pk_mul_f32 v[64:65], v[120:121], v[92:93]
	v_pk_fma_f32 v[56:57], v[92:93], v[146:147], v[56:57]
	v_pk_fma_f32 v[64:65], v[118:119], v[90:91], v[64:65]
	v_add_f32_e32 v58, v56, v57
	v_add_f32_e32 v66, v64, v65
	v_pk_mul_f32 v[60:61], v[160:161], v[152:153] op_sel_hi:[0,1]
	v_add_f32_dpp v58, v58, v58 quad_perm:[1,0,3,2] row_mask:0xf bank_mask:0xf bound_ctrl:1
	v_add_f32_dpp v66, v66, v66 quad_perm:[1,0,3,2] row_mask:0xf bank_mask:0xf bound_ctrl:1
	v_pk_fma_f32 v[60:61], v[90:91], v[148:149], v[60:61]
	v_add_f32_dpp v58, v58, v58 quad_perm:[2,3,0,1] row_mask:0xf bank_mask:0xf bound_ctrl:1
	v_add_f32_dpp v66, v66, v66 quad_perm:[2,3,0,1] row_mask:0xf bank_mask:0xf bound_ctrl:1
	v_pk_mul_f32 v[62:63], v[160:161], v[154:155] op_sel_hi:[0,1]
	v_add_f32_dpp v58, v58, v58 row_half_mirror row_mask:0xf bank_mask:0xf bound_ctrl:1
	v_add_f32_dpp v66, v66, v66 row_half_mirror row_mask:0xf bank_mask:0xf bound_ctrl:1
	v_pk_fma_f32 v[62:63], v[92:93], v[150:151], v[62:63]
	v_add_f32_dpp v58, v58, v58 row_mirror row_mask:0xf bank_mask:0xf bound_ctrl:1
	v_add_f32_dpp v66, v66, v66 row_mirror row_mask:0xf bank_mask:0xf bound_ctrl:1
	v_pk_fma_f32 v[90:91], v[156:157], v[58:59], v[60:61] op_sel_hi:[1,0,1] neg_lo:[1,0,0] neg_hi:[1,0,0]
	v_pk_fma_f32 v[92:93], v[158:159], v[58:59], v[62:63] op_sel_hi:[1,0,1] neg_lo:[1,0,0] neg_hi:[1,0,0]
	v_cndmask_b32_e64 v67, v67, v66, s[50:51]
	s_waitcnt lgkmcnt(6)
; DI void scan_item(const Params& p, int item, char* smem) {
;     ...
;     for (int st = 0; st < 16; st++) {
;       StepIn nxt = cur;
;       if (st + 1 < 16) nxt = ldstep(base + (st + 1) * 6 * 64);
;       __builtin_amdgcn_sched_barrier(0);
;       f32x2 ra = {cur.r.x, cur.r.y}, rb = {cur.r.z, cur.r.w}, ka = {cur.k.x, cur.k.y}, kb = {cur.k.z, cur.k.w};
;       f32x2 wa = {cur.w.x, cur.w.y}, wb = {cur.w.z, cur.w.w}, da = {cur.d.x, cur.d.y}, db = {cur.d.z, cur.d.w};
;       f32x2 ba = {cur.b.x, cur.b.y}, bb2 = {cur.b.z, cur.b.w};
;       f32x2 pp = Sa * ka + Sb * kb;
;       float sa = allreduce16(pp.x + pp.y);
;       f32x2 vv2 = {cur.v, cur.v};
;       f32x2 sa2 = {sa, sa};
;       Sa = (Sa * wa + vv2 * da) - sa2 * ba;
;       Sb = (Sb * wb + vv2 * db) - sa2 * bb2;
;       f32x2 yy = Sa * ra + Sb * rb;
;       float y = allreduce16(yy.x + yy.y);
;       ykeep = (l16 == st) ? y : ykeep;
;       cur = nxt;
	ds_read_b128 v[122:125], v49 offset:15616
	ds_read_b32 v138, v50 offset:15872
	ds_read_b128 v[130:133], v49 offset:16384
	ds_read_b128 v[126:129], v49 offset:16128
	ds_read_b128 v[134:137], v49 offset:16640
	ds_read_b128 v[118:121], v49 offset:15360
	v_pk_mul_f32 v[56:57], v[90:91], v[72:73]
	v_pk_mul_f32 v[64:65], v[142:143], v[92:93]
	v_pk_fma_f32 v[56:57], v[92:93], v[74:75], v[56:57]
	v_pk_fma_f32 v[64:65], v[140:141], v[90:91], v[64:65]
	v_add_f32_e32 v58, v56, v57
	v_add_f32_e32 v66, v64, v65
	v_pk_mul_f32 v[60:61], v[88:89], v[80:81] op_sel_hi:[0,1]
	v_add_f32_dpp v58, v58, v58 quad_perm:[1,0,3,2] row_mask:0xf bank_mask:0xf bound_ctrl:1
	v_add_f32_dpp v66, v66, v66 quad_perm:[1,0,3,2] row_mask:0xf bank_mask:0xf bound_ctrl:1
	v_pk_fma_f32 v[60:61], v[90:91], v[76:77], v[60:61]
	v_add_f32_dpp v58, v58, v58 quad_perm:[2,3,0,1] row_mask:0xf bank_mask:0xf bound_ctrl:1
	v_add_f32_dpp v66, v66, v66 quad_perm:[2,3,0,1] row_mask:0xf bank_mask:0xf bound_ctrl:1
	v_pk_mul_f32 v[62:63], v[88:89], v[82:83] op_sel_hi:[0,1]
	v_add_f32_dpp v58, v58, v58 row_half_mirror row_mask:0xf bank_mask:0xf bound_ctrl:1
	v_add_f32_dpp v66, v66, v66 row_half_mirror row_mask:0xf bank_mask:0xf bound_ctrl:1
	v_pk_fma_f32 v[62:63], v[92:93], v[78:79], v[62:63]
	v_add_f32_dpp v58, v58, v58 row_mirror row_mask:0xf bank_mask:0xf bound_ctrl:1
	v_add_f32_dpp v66, v66, v66 row_mirror row_mask:0xf bank_mask:0xf bound_ctrl:1
	v_pk_fma_f32 v[90:91], v[84:85], v[58:59], v[60:61] op_sel_hi:[1,0,1] neg_lo:[1,0,0] neg_hi:[1,0,0]
	v_pk_fma_f32 v[92:93], v[86:87], v[58:59], v[62:63] op_sel_hi:[1,0,1] neg_lo:[1,0,0] neg_hi:[1,0,0]
	v_cndmask_b32_e64 v67, v67, v66, s[52:53]
	s_waitcnt lgkmcnt(6)
	ds_read_b128 v[144:147], v49 offset:17152
	ds_read_b32 v160, v50 offset:17408
	ds_read_b128 v[152:155], v49 offset:17920
	ds_read_b128 v[148:151], v49 offset:17664
	ds_read_b128 v[156:159], v49 offset:18176
	ds_read_b128 v[140:143], v49 offset:16896
	v_pk_mul_f32 v[56:57], v[90:91], v[100:101]
	v_pk_mul_f32 v[64:65], v[70:71], v[92:93]
	v_pk_fma_f32 v[56:57], v[92:93], v[102:103], v[56:57]
	v_pk_fma_f32 v[64:65], v[68:69], v[90:91], v[64:65]
	v_add_f32_e32 v58, v56, v57
	v_add_f32_e32 v66, v64, v65
	v_pk_mul_f32 v[60:61], v[116:117], v[108:109] op_sel_hi:[0,1]
	v_add_f32_dpp v58, v58, v58 quad_perm:[1,0,3,2] row_mask:0xf bank_mask:0xf bound_ctrl:1
	v_add_f32_dpp v66, v66, v66 quad_perm:[1,0,3,2] row_mask:0xf bank_mask:0xf bound_ctrl:1
	v_pk_fma_f32 v[60:61], v[90:91], v[104:105], v[60:61]
	v_add_f32_dpp v58, v58, v58 quad_perm:[2,3,0,1] row_mask:0xf bank_mask:0xf bound_ctrl:1
	v_add_f32_dpp v66, v66, v66 quad_perm:[2,3,0,1] row_mask:0xf bank_mask:0xf bound_ctrl:1
	v_pk_mul_f32 v[62:63], v[116:117], v[110:111] op_sel_hi:[0,1]
	v_add_f32_dpp v58, v58, v58 row_half_mirror row_mask:0xf bank_mask:0xf bound_ctrl:1
	v_add_f32_dpp v66, v66, v66 row_half_mirror row_mask:0xf bank_mask:0xf bound_ctrl:1
	v_pk_fma_f32 v[62:63], v[92:93], v[106:107], v[62:63]
	v_add_f32_dpp v58, v58, v58 row_mirror row_mask:0xf bank_mask:0xf bound_ctrl:1
	v_add_f32_dpp v66, v66, v66 row_mirror row_mask:0xf bank_mask:0xf bound_ctrl:1
	v_pk_fma_f32 v[90:91], v[112:113], v[58:59], v[60:61] op_sel_hi:[1,0,1] neg_lo:[1,0,0] neg_hi:[1,0,0]
	v_pk_fma_f32 v[92:93], v[114:115], v[58:59], v[62:63] op_sel_hi:[1,0,1] neg_lo:[1,0,0] neg_hi:[1,0,0]
	v_cndmask_b32_e64 v67, v67, v66, s[54:55]
	s_waitcnt lgkmcnt(6)
	ds_read_b128 v[72:75], v49 offset:18688
	ds_read_b32 v88, v50 offset:18944
	ds_read_b128 v[80:83], v49 offset:19456
	ds_read_b128 v[76:79], v49 offset:19200
	ds_read_b128 v[84:87], v49 offset:19712
	ds_read_b128 v[68:71], v49 offset:18432
	v_pk_mul_f32 v[56:57], v[90:91], v[122:123]
	v_pk_mul_f32 v[64:65], v[98:99], v[92:93]
	v_pk_fma_f32 v[56:57], v[92:93], v[124:125], v[56:57]
	v_pk_fma_f32 v[64:65], v[96:97], v[90:91], v[64:65]
	v_add_f32_e32 v58, v56, v57
	v_add_f32_e32 v66, v64, v65
	v_pk_mul_f32 v[60:61], v[138:139], v[130:131] op_sel_hi:[0,1]
	v_add_f32_dpp v58, v58, v58 quad_perm:[1,0,3,2] row_mask:0xf bank_mask:0xf bound_ctrl:1
	v_add_f32_dpp v66, v66, v66 quad_perm:[1,0,3,2] row_mask:0xf bank_mask:0xf bound_ctrl:1
	v_pk_fma_f32 v[60:61], v[90:91], v[126:127], v[60:61]
	v_add_f32_dpp v58, v58, v58 quad_perm:[2,3,0,1] row_mask:0xf bank_mask:0xf bound_ctrl:1
	v_add_f32_dpp v66, v66, v66 quad_perm:[2,3,0,1] row_mask:0xf bank_mask:0xf bound_ctrl:1
	v_pk_mul_f32 v[62:63], v[138:139], v[132:133] op_sel_hi:[0,1]
	v_add_f32_dpp v58, v58, v58 row_half_mirror row_mask:0xf bank_mask:0xf bound_ctrl:1
	v_add_f32_dpp v66, v66, v66 row_half_mirror row_mask:0xf bank_mask:0xf bound_ctrl:1
	v_pk_fma_f32 v[62:63], v[92:93], v[128:129], v[62:63]
	v_add_f32_dpp v58, v58, v58 row_mirror row_mask:0xf bank_mask:0xf bound_ctrl:1
	v_add_f32_dpp v66, v66, v66 row_mirror row_mask:0xf bank_mask:0xf bound_ctrl:1
	v_pk_fma_f32 v[90:91], v[134:135], v[58:59], v[60:61] op_sel_hi:[1,0,1] neg_lo:[1,0,0] neg_hi:[1,0,0]
	v_pk_fma_f32 v[92:93], v[136:137], v[58:59], v[62:63] op_sel_hi:[1,0,1] neg_lo:[1,0,0] neg_hi:[1,0,0]
	v_cndmask_b32_e64 v67, v67, v66, s[56:57]
	s_waitcnt lgkmcnt(6)
; DI void scan_item(const Params& p, int item, char* smem) {
;     ...
;     for (int st = 0; st < 16; st++) {
;       StepIn nxt = cur;
;       if (st + 1 < 16) nxt = ldstep(base + (st + 1) * 6 * 64);
;       __builtin_amdgcn_sched_barrier(0);
;       f32x2 ra = {cur.r.x, cur.r.y}, rb = {cur.r.z, cur.r.w}, ka = {cur.k.x, cur.k.y}, kb = {cur.k.z, cur.k.w};
;       f32x2 wa = {cur.w.x, cur.w.y}, wb = {cur.w.z, cur.w.w}, da = {cur.d.x, cur.d.y}, db = {cur.d.z, cur.d.w};
;       f32x2 ba = {cur.b.x, cur.b.y}, bb2 = {cur.b.z, cur.b.w};
;       f32x2 pp = Sa * ka + Sb * kb;
;       float sa = allreduce16(pp.x + pp.y);
;       f32x2 vv2 = {cur.v, cur.v};
;       f32x2 sa2 = {sa, sa};
;       Sa = (Sa * wa + vv2 * da) - sa2 * ba;
;       Sb = (Sb * wb + vv2 * db) - sa2 * bb2;
;       f32x2 yy = Sa * ra + Sb * rb;
;       float y = allreduce16(yy.x + yy.y);
;       ykeep = (l16 == st) ? y : ykeep;
;       cur = nxt;
	ds_read_b128 v[100:103], v49 offset:20224
	ds_read_b32 v116, v50 offset:20480
	ds_read_b128 v[108:111], v49 offset:20992
	ds_read_b128 v[104:107], v49 offset:20736
	ds_read_b128 v[112:115], v49 offset:21248
	ds_read_b128 v[96:99], v49 offset:19968
	v_pk_mul_f32 v[56:57], v[90:91], v[144:145]
	v_pk_mul_f32 v[64:65], v[120:121], v[92:93]
	v_pk_fma_f32 v[56:57], v[92:93], v[146:147], v[56:57]
	v_pk_fma_f32 v[64:65], v[118:119], v[90:91], v[64:65]
	v_add_f32_e32 v58, v56, v57
	v_add_f32_e32 v66, v64, v65
	v_pk_mul_f32 v[60:61], v[160:161], v[152:153] op_sel_hi:[0,1]
	v_add_f32_dpp v58, v58, v58 quad_perm:[1,0,3,2] row_mask:0xf bank_mask:0xf bound_ctrl:1
	v_add_f32_dpp v66, v66, v66 quad_perm:[1,0,3,2] row_mask:0xf bank_mask:0xf bound_ctrl:1
	v_pk_fma_f32 v[60:61], v[90:91], v[148:149], v[60:61]
	v_add_f32_dpp v58, v58, v58 quad_perm:[2,3,0,1] row_mask:0xf bank_mask:0xf bound_ctrl:1
	v_add_f32_dpp v66, v66, v66 quad_perm:[2,3,0,1] row_mask:0xf bank_mask:0xf bound_ctrl:1
	v_pk_mul_f32 v[62:63], v[160:161], v[154:155] op_sel_hi:[0,1]
	v_add_f32_dpp v58, v58, v58 row_half_mirror row_mask:0xf bank_mask:0xf bound_ctrl:1
	v_add_f32_dpp v66, v66, v66 row_half_mirror row_mask:0xf bank_mask:0xf bound_ctrl:1
	v_pk_fma_f32 v[62:63], v[92:93], v[150:151], v[62:63]
	v_add_f32_dpp v58, v58, v58 row_mirror row_mask:0xf bank_mask:0xf bound_ctrl:1
	v_add_f32_dpp v66, v66, v66 row_mirror row_mask:0xf bank_mask:0xf bound_ctrl:1
	v_pk_fma_f32 v[90:91], v[156:157], v[58:59], v[60:61] op_sel_hi:[1,0,1] neg_lo:[1,0,0] neg_hi:[1,0,0]
	v_pk_fma_f32 v[92:93], v[158:159], v[58:59], v[62:63] op_sel_hi:[1,0,1] neg_lo:[1,0,0] neg_hi:[1,0,0]
	v_cndmask_b32_e64 v67, v67, v66, s[58:59]
	s_waitcnt lgkmcnt(6)
	ds_read_b128 v[122:125], v49 offset:21760
	ds_read_b32 v138, v50 offset:22016
	ds_read_b128 v[130:133], v49 offset:22528
	ds_read_b128 v[126:129], v49 offset:22272
	ds_read_b128 v[134:137], v49 offset:22784
	ds_read_b128 v[118:121], v49 offset:21504
	v_pk_mul_f32 v[56:57], v[90:91], v[72:73]
	v_pk_mul_f32 v[64:65], v[142:143], v[92:93]
	v_pk_fma_f32 v[56:57], v[92:93], v[74:75], v[56:57]
	v_pk_fma_f32 v[64:65], v[140:141], v[90:91], v[64:65]
	v_add_f32_e32 v58, v56, v57
	v_add_f32_e32 v66, v64, v65
	v_pk_mul_f32 v[60:61], v[88:89], v[80:81] op_sel_hi:[0,1]
	v_add_f32_dpp v58, v58, v58 quad_perm:[1,0,3,2] row_mask:0xf bank_mask:0xf bound_ctrl:1
	v_add_f32_dpp v66, v66, v66 quad_perm:[1,0,3,2] row_mask:0xf bank_mask:0xf bound_ctrl:1
	v_pk_fma_f32 v[60:61], v[90:91], v[76:77], v[60:61]
	v_add_f32_dpp v58, v58, v58 quad_perm:[2,3,0,1] row_mask:0xf bank_mask:0xf bound_ctrl:1
	v_add_f32_dpp v66, v66, v66 quad_perm:[2,3,0,1] row_mask:0xf bank_mask:0xf bound_ctrl:1
	v_pk_mul_f32 v[62:63], v[88:89], v[82:83] op_sel_hi:[0,1]
	v_add_f32_dpp v58, v58, v58 row_half_mirror row_mask:0xf bank_mask:0xf bound_ctrl:1
	v_add_f32_dpp v66, v66, v66 row_half_mirror row_mask:0xf bank_mask:0xf bound_ctrl:1
	v_pk_fma_f32 v[62:63], v[92:93], v[78:79], v[62:63]
	v_add_f32_dpp v58, v58, v58 row_mirror row_mask:0xf bank_mask:0xf bound_ctrl:1
	v_add_f32_dpp v66, v66, v66 row_mirror row_mask:0xf bank_mask:0xf bound_ctrl:1
	v_pk_fma_f32 v[90:91], v[84:85], v[58:59], v[60:61] op_sel_hi:[1,0,1] neg_lo:[1,0,0] neg_hi:[1,0,0]
	v_pk_fma_f32 v[92:93], v[86:87], v[58:59], v[62:63] op_sel_hi:[1,0,1] neg_lo:[1,0,0] neg_hi:[1,0,0]
	v_cndmask_b32_e64 v67, v67, v66, s[60:61]
	s_waitcnt lgkmcnt(6)
	ds_read_b128 v[144:147], v49 offset:23296
	ds_read_b32 v160, v50 offset:23552
	ds_read_b128 v[152:155], v49 offset:24064
	ds_read_b128 v[148:151], v49 offset:23808
	ds_read_b128 v[156:159], v49 offset:24320
	ds_read_b128 v[140:143], v49 offset:23040
	v_pk_mul_f32 v[56:57], v[90:91], v[100:101]
	v_pk_mul_f32 v[64:65], v[70:71], v[92:93]
	v_pk_fma_f32 v[56:57], v[92:93], v[102:103], v[56:57]
	v_pk_fma_f32 v[64:65], v[68:69], v[90:91], v[64:65]
	v_add_f32_e32 v58, v56, v57
	v_add_f32_e32 v66, v64, v65
	v_pk_mul_f32 v[60:61], v[116:117], v[108:109] op_sel_hi:[0,1]
	v_add_f32_dpp v58, v58, v58 quad_perm:[1,0,3,2] row_mask:0xf bank_mask:0xf bound_ctrl:1
	v_add_f32_dpp v66, v66, v66 quad_perm:[1,0,3,2] row_mask:0xf bank_mask:0xf bound_ctrl:1
	v_pk_fma_f32 v[60:61], v[90:91], v[104:105], v[60:61]
	v_add_f32_dpp v58, v58, v58 quad_perm:[2,3,0,1] row_mask:0xf bank_mask:0xf bound_ctrl:1
	v_add_f32_dpp v66, v66, v66 quad_perm:[2,3,0,1] row_mask:0xf bank_mask:0xf bound_ctrl:1
	v_pk_mul_f32 v[62:63], v[116:117], v[110:111] op_sel_hi:[0,1]
	v_add_f32_dpp v58, v58, v58 row_half_mirror row_mask:0xf bank_mask:0xf bound_ctrl:1
	v_add_f32_dpp v66, v66, v66 row_half_mirror row_mask:0xf bank_mask:0xf bound_ctrl:1
	v_pk_fma_f32 v[62:63], v[92:93], v[106:107], v[62:63]
	v_add_f32_dpp v58, v58, v58 row_mirror row_mask:0xf bank_mask:0xf bound_ctrl:1
	v_add_f32_dpp v66, v66, v66 row_mirror row_mask:0xf bank_mask:0xf bound_ctrl:1
	v_pk_fma_f32 v[90:91], v[112:113], v[58:59], v[60:61] op_sel_hi:[1,0,1] neg_lo:[1,0,0] neg_hi:[1,0,0]
	v_pk_fma_f32 v[92:93], v[114:115], v[58:59], v[62:63] op_sel_hi:[1,0,1] neg_lo:[1,0,0] neg_hi:[1,0,0]
	v_cndmask_b32_e64 v67, v67, v66, s[62:63]
	s_waitcnt lgkmcnt(6)
; DI void scan_item(const Params& p, int item, char* smem) {
;     ...
;   auto lstore = [&](int buf) {
; #pragma unroll
;     for (int i = 0; i < 3; i++) {
;       int id = tid + i * 256;
;       int st = id / 48, rem = id % 48, vec = rem >> 3, part = rem & 7;
;       h8 hv = __builtin_bit_cast(h8, rg_[i]);
;       f8 fv = __builtin_convertvector(hv, f8);
;       float* d = sIn + ((buf * 16 + st) * 6 + vec) * 64 + part * 8;
;       *(f32x4v*)d = f32x4v{fv[0], fv[1], fv[2], fv[3]};
;       *(f32x4v*)(d + 4) = f32x4v{fv[4], fv[5], fv[6], fv[7]};
;     }
;   };
;     ...
;     for (int st = 0; st < 16; st++) {
;       StepIn nxt = cur;
;       if (st + 1 < 16) nxt = ldstep(base + (st + 1) * 6 * 64);
;       __builtin_amdgcn_sched_barrier(0);
;       f32x2 ra = {cur.r.x, cur.r.y}, rb = {cur.r.z, cur.r.w}, ka = {cur.k.x, cur.k.y}, kb = {cur.k.z, cur.k.w};
;       f32x2 wa = {cur.w.x, cur.w.y}, wb = {cur.w.z, cur.w.w}, da = {cur.d.x, cur.d.y}, db = {cur.d.z, cur.d.w};
;       f32x2 ba = {cur.b.x, cur.b.y}, bb2 = {cur.b.z, cur.b.w};
;       f32x2 pp = Sa * ka + Sb * kb;
;       float sa = allreduce16(pp.x + pp.y);
;       f32x2 vv2 = {cur.v, cur.v};
;       f32x2 sa2 = {sa, sa};
;       Sa = (Sa * wa + vv2 * da) - sa2 * ba;
;       Sb = (Sb * wb + vv2 * db) - sa2 * bb2;
;       f32x2 yy = Sa * ra + Sb * rb;
;       float y = allreduce16(yy.x + yy.y);
;       ykeep = (l16 == st) ? y : ykeep;
;       cur = nxt;
;     }
;     { _Float16 yh = (_Float16)ykeep; yb[(long)tof(ci * 16 + l16) * 256 + rowl] = __builtin_bit_cast(u16, yh); }
;     if (ci + 1 < nch) lstore((ci + 1) & 1);
;     __syncthreads();
;   }
	v_pk_mul_f32 v[56:57], v[90:91], v[122:123]
	v_pk_mul_f32 v[64:65], v[98:99], v[92:93]
	v_pk_fma_f32 v[56:57], v[92:93], v[124:125], v[56:57]
	v_pk_fma_f32 v[64:65], v[96:97], v[90:91], v[64:65]
	v_add_f32_e32 v58, v56, v57
	v_add_f32_e32 v66, v64, v65
	v_pk_mul_f32 v[60:61], v[138:139], v[130:131] op_sel_hi:[0,1]
	v_add_f32_dpp v58, v58, v58 quad_perm:[1,0,3,2] row_mask:0xf bank_mask:0xf bound_ctrl:1
	v_add_f32_dpp v66, v66, v66 quad_perm:[1,0,3,2] row_mask:0xf bank_mask:0xf bound_ctrl:1
	v_pk_fma_f32 v[60:61], v[90:91], v[126:127], v[60:61]
	v_add_f32_dpp v58, v58, v58 quad_perm:[2,3,0,1] row_mask:0xf bank_mask:0xf bound_ctrl:1
	v_add_f32_dpp v66, v66, v66 quad_perm:[2,3,0,1] row_mask:0xf bank_mask:0xf bound_ctrl:1
	v_pk_mul_f32 v[62:63], v[138:139], v[132:133] op_sel_hi:[0,1]
	v_add_f32_dpp v58, v58, v58 row_half_mirror row_mask:0xf bank_mask:0xf bound_ctrl:1
	v_add_f32_dpp v66, v66, v66 row_half_mirror row_mask:0xf bank_mask:0xf bound_ctrl:1
	v_pk_fma_f32 v[62:63], v[92:93], v[128:129], v[62:63]
	v_add_f32_dpp v58, v58, v58 row_mirror row_mask:0xf bank_mask:0xf bound_ctrl:1
	v_add_f32_dpp v66, v66, v66 row_mirror row_mask:0xf bank_mask:0xf bound_ctrl:1
	v_pk_fma_f32 v[90:91], v[134:135], v[58:59], v[60:61] op_sel_hi:[1,0,1] neg_lo:[1,0,0] neg_hi:[1,0,0]
	v_pk_fma_f32 v[92:93], v[136:137], v[58:59], v[62:63] op_sel_hi:[1,0,1] neg_lo:[1,0,0] neg_hi:[1,0,0]
	v_cndmask_b32_e64 v67, v67, v66, s[64:65]
	s_waitcnt lgkmcnt(0)
	v_pk_mul_f32 v[56:57], v[90:91], v[144:145]
	v_pk_mul_f32 v[64:65], v[120:121], v[92:93]
	v_pk_fma_f32 v[56:57], v[92:93], v[146:147], v[56:57]
	v_pk_fma_f32 v[64:65], v[118:119], v[90:91], v[64:65]
	v_add_f32_e32 v58, v56, v57
	v_add_f32_e32 v66, v64, v65
	v_pk_mul_f32 v[60:61], v[160:161], v[152:153] op_sel_hi:[0,1]
	v_add_f32_dpp v58, v58, v58 quad_perm:[1,0,3,2] row_mask:0xf bank_mask:0xf bound_ctrl:1
	v_add_f32_dpp v66, v66, v66 quad_perm:[1,0,3,2] row_mask:0xf bank_mask:0xf bound_ctrl:1
	v_pk_fma_f32 v[60:61], v[90:91], v[148:149], v[60:61]
	v_add_f32_dpp v58, v58, v58 quad_perm:[2,3,0,1] row_mask:0xf bank_mask:0xf bound_ctrl:1
	v_add_f32_dpp v66, v66, v66 quad_perm:[2,3,0,1] row_mask:0xf bank_mask:0xf bound_ctrl:1
	v_pk_mul_f32 v[62:63], v[160:161], v[154:155] op_sel_hi:[0,1]
	v_add_f32_dpp v58, v58, v58 row_half_mirror row_mask:0xf bank_mask:0xf bound_ctrl:1
	v_add_f32_dpp v66, v66, v66 row_half_mirror row_mask:0xf bank_mask:0xf bound_ctrl:1
	v_pk_fma_f32 v[62:63], v[92:93], v[150:151], v[62:63]
	v_add_f32_dpp v58, v58, v58 row_mirror row_mask:0xf bank_mask:0xf bound_ctrl:1
	v_add_f32_dpp v66, v66, v66 row_mirror row_mask:0xf bank_mask:0xf bound_ctrl:1
	v_pk_fma_f32 v[90:91], v[156:157], v[58:59], v[60:61] op_sel_hi:[1,0,1] neg_lo:[1,0,0] neg_hi:[1,0,0]
	v_pk_fma_f32 v[92:93], v[158:159], v[58:59], v[62:63] op_sel_hi:[1,0,1] neg_lo:[1,0,0] neg_hi:[1,0,0]
	v_cndmask_b32_e64 v67, v67, v66, s[66:67]
	s_nop 0
	v_pk_mul_f32 v[64:65], v[142:143], v[92:93]
	s_cmpk_gt_u32 s26, 0xff
	s_movk_i32 s12, 0x11ff
	s_cselect_b32 s12, s12, 0xff
	v_pk_fma_f32 v[64:65], v[140:141], v[90:91], v[64:65]
	s_sub_i32 s12, s12, s26
	v_add_u32_e32 v46, s26, v36
	v_add_f32_e32 v66, v64, v65
	v_sub_u32_e32 v47, s12, v36
	v_cndmask_b32_e64 v46, v47, v46, s[36:37]
	v_add_f32_dpp v66, v66, v66 quad_perm:[1,0,3,2] row_mask:0xf bank_mask:0xf bound_ctrl:1
	v_mov_b32_e32 v47, 0
	v_lshlrev_b64 v[46:47], 9, v[46:47]
	v_add_f32_dpp v66, v66, v66 quad_perm:[2,3,0,1] row_mask:0xf bank_mask:0xf bound_ctrl:1
	v_lshl_add_u64 v[46:47], v[30:31], 0, v[46:47]
	s_nop 0
	v_add_f32_dpp v66, v66, v66 row_half_mirror row_mask:0xf bank_mask:0xf bound_ctrl:1
	s_nop 1
	v_add_f32_dpp v66, v66, v66 row_mirror row_mask:0xf bank_mask:0xf bound_ctrl:1
	v_cndmask_b32_e64 v67, v67, v66, s[68:69]
	v_cvt_f16_f32_e32 v45, v67
	global_store_short v[46:47], v45, off
	s_waitcnt vmcnt(6)
	v_cvt_f32_f16_e32 v40, v0
	v_cvt_f32_f16_sdwa v41, v0 dst_sel:DWORD dst_unused:UNUSED_PAD src0_sel:WORD_1
	v_cvt_f32_f16_e32 v42, v1
	v_cvt_f32_f16_sdwa v43, v1 dst_sel:DWORD dst_unused:UNUSED_PAD src0_sel:WORD_1
	v_cvt_f32_f16_e32 v44, v2
	v_cvt_f32_f16_sdwa v45, v2 dst_sel:DWORD dst_unused:UNUSED_PAD src0_sel:WORD_1
	v_cvt_f32_f16_e32 v46, v3
	v_cvt_f32_f16_sdwa v47, v3 dst_sel:DWORD dst_unused:UNUSED_PAD src0_sel:WORD_1
	ds_write_b128 v32, v[40:43] offset:24576
	ds_write_b128 v32, v[44:47] offset:24592
	s_waitcnt vmcnt(5)
	v_cvt_f32_f16_e32 v40, v4
	v_cvt_f32_f16_sdwa v41, v4 dst_sel:DWORD dst_unused:UNUSED_PAD src0_sel:WORD_1
	v_cvt_f32_f16_e32 v42, v5
	v_cvt_f32_f16_sdwa v43, v5 dst_sel:DWORD dst_unused:UNUSED_PAD src0_sel:WORD_1
	v_cvt_f32_f16_e32 v44, v6
	v_cvt_f32_f16_sdwa v45, v6 dst_sel:DWORD dst_unused:UNUSED_PAD src0_sel:WORD_1
	v_cvt_f32_f16_e32 v46, v7
	v_cvt_f32_f16_sdwa v47, v7 dst_sel:DWORD dst_unused:UNUSED_PAD src0_sel:WORD_1
	ds_write_b128 v33, v[40:43] offset:24576
	ds_write_b128 v33, v[44:47] offset:24592
	s_waitcnt vmcnt(4)
	v_cvt_f32_f16_e32 v40, v8
	v_cvt_f32_f16_sdwa v41, v8 dst_sel:DWORD dst_unused:UNUSED_PAD src0_sel:WORD_1
	v_cvt_f32_f16_e32 v42, v9
	v_cvt_f32_f16_sdwa v43, v9 dst_sel:DWORD dst_unused:UNUSED_PAD src0_sel:WORD_1
	v_cvt_f32_f16_e32 v44, v10
	v_cvt_f32_f16_sdwa v45, v10 dst_sel:DWORD dst_unused:UNUSED_PAD src0_sel:WORD_1
	v_cvt_f32_f16_e32 v46, v11
	v_cvt_f32_f16_sdwa v47, v11 dst_sel:DWORD dst_unused:UNUSED_PAD src0_sel:WORD_1
	ds_write_b128 v34, v[40:43] offset:24576
	ds_write_b128 v34, v[44:47] offset:24592
	s_add_i32 s26, s26, 16
	s_waitcnt lgkmcnt(0)
	s_barrier
; DI void scan_item(const Params& p, int item, char* smem) {
;     ...
;   auto gload = [&](int ci) {
; #pragma unroll
;     for (int i = 0; i < 3; i++) {
;       int id = tid + i * 256;
;       int st = id / 48, rem = id % 48, vec = rem >> 3, part = rem & 7;
;       int t = tof(ci * 16 + st);
;       int vi = vec < 3 ? vec : vec + 3 * dir;
;       rg_[i] = *(const u32x4*)(SIb + ((long)t * 9 + vi) * 64 + part * 8);
;     }
;   };
;     ...
;     for (int st = 0; st < 16; st++) {
;       StepIn nxt = cur;
;       if (st + 1 < 16) nxt = ldstep(base + (st + 1) * 6 * 64);
;       __builtin_amdgcn_sched_barrier(0);
;       f32x2 ra = {cur.r.x, cur.r.y}, rb = {cur.r.z, cur.r.w}, ka = {cur.k.x, cur.k.y}, kb = {cur.k.z, cur.k.w};
;       f32x2 wa = {cur.w.x, cur.w.y}, wb = {cur.w.z, cur.w.w}, da = {cur.d.x, cur.d.y}, db = {cur.d.z, cur.d.w};
;       f32x2 ba = {cur.b.x, cur.b.y}, bb2 = {cur.b.z, cur.b.w};
;       f32x2 pp = Sa * ka + Sb * kb;
;       float sa = allreduce16(pp.x + pp.y);
;       f32x2 vv2 = {cur.v, cur.v};
;       f32x2 sa2 = {sa, sa};
;       Sa = (Sa * wa + vv2 * da) - sa2 * ba;
;       Sb = (Sb * wb + vv2 * db) - sa2 * bb2;
;       f32x2 yy = Sa * ra + Sb * rb;
;       float y = allreduce16(yy.x + yy.y);
;       ykeep = (l16 == st) ? y : ykeep;
;       cur = nxt;
	ds_read_b128 v[72:75], v49 offset:24832
	ds_read_b32 v88, v50 offset:25088
	ds_read_b128 v[80:83], v49 offset:25600
	ds_read_b128 v[76:79], v49 offset:25344
	ds_read_b128 v[84:87], v49 offset:25856
	ds_read_b128 v[68:71], v49 offset:24576
	ds_read_b128 v[100:103], v49 offset:26368
	ds_read_b32 v116, v50 offset:26624
	ds_read_b128 v[108:111], v49 offset:27136
	ds_read_b128 v[104:107], v49 offset:26880
	ds_read_b128 v[112:115], v49 offset:27392
	ds_read_b128 v[96:99], v49 offset:26112
	s_add_i32 s72, s26, 32
	s_min_u32 s72, s72, 0x10f0
	v_add_u32_e32 v0, s72, v13
	v_add_u32_e32 v4, s72, v17
	v_add_u32_e32 v8, s72, v21
	v_cmp_lt_i32_e32 vcc, 0xff, v0
	s_nop 1
	v_cndmask_b32_e32 v1, v208, v209, vcc
	v_cmp_lt_i32_e32 vcc, 0xff, v4
	v_sub_u32_e32 v1, v1, v0
	v_cndmask_b32_e64 v0, v1, v0, s[36:37]
	v_cndmask_b32_e32 v5, v208, v209, vcc
	v_cmp_lt_i32_e32 vcc, 0xff, v8
	v_sub_u32_e32 v5, v5, v4
	v_cndmask_b32_e64 v4, v5, v4, s[36:37]
	v_cndmask_b32_e32 v9, v208, v209, vcc
	v_sub_u32_e32 v9, v9, v8
	v_cndmask_b32_e64 v8, v9, v8, s[36:37]
	v_mad_i64_i32 v[0:1], s[12:13], v0, 9, v[14:15]
	v_mad_i64_i32 v[4:5], s[12:13], v4, 9, v[18:19]
	v_mad_i64_i32 v[8:9], s[12:13], v8, 9, v[22:23]
	v_lshlrev_b64 v[0:1], 7, v[0:1]
	v_lshlrev_b64 v[4:5], 7, v[4:5]
	v_lshlrev_b64 v[8:9], 7, v[8:9]
	v_lshl_add_u64 v[0:1], v[24:25], 0, v[0:1]
	v_lshl_add_u64 v[4:5], v[26:27], 0, v[4:5]
	v_lshl_add_u64 v[8:9], v[28:29], 0, v[8:9]
	global_load_dwordx4 v[0:3], v[0:1], off
	global_load_dwordx4 v[4:7], v[4:5], off
	global_load_dwordx4 v[8:11], v[8:9], off
	s_waitcnt lgkmcnt(6)
	ds_read_b128 v[122:125], v49 offset:27904
	ds_read_b32 v138, v50 offset:28160
	ds_read_b128 v[130:133], v49 offset:28672
	ds_read_b128 v[126:129], v49 offset:28416
	ds_read_b128 v[134:137], v49 offset:28928
	ds_read_b128 v[118:121], v49 offset:27648
	v_pk_mul_f32 v[56:57], v[90:91], v[72:73]
	v_pk_mul_f32 v[60:61], v[88:89], v[80:81] op_sel_hi:[0,1]
	v_pk_fma_f32 v[56:57], v[92:93], v[74:75], v[56:57]
	v_pk_mul_f32 v[62:63], v[88:89], v[82:83] op_sel_hi:[0,1]
	v_add_f32_e32 v58, v56, v57
	v_pk_fma_f32 v[60:61], v[90:91], v[76:77], v[60:61]
	v_pk_fma_f32 v[62:63], v[92:93], v[78:79], v[62:63]
	v_add_f32_dpp v58, v58, v58 quad_perm:[1,0,3,2] row_mask:0xf bank_mask:0xf bound_ctrl:1
	s_nop 1
	v_add_f32_dpp v58, v58, v58 quad_perm:[2,3,0,1] row_mask:0xf bank_mask:0xf bound_ctrl:1
	s_nop 1
	v_add_f32_dpp v58, v58, v58 row_half_mirror row_mask:0xf bank_mask:0xf bound_ctrl:1
	s_nop 1
	v_add_f32_dpp v58, v58, v58 row_mirror row_mask:0xf bank_mask:0xf bound_ctrl:1
	s_nop 0
	v_pk_fma_f32 v[90:91], v[84:85], v[58:59], v[60:61] op_sel_hi:[1,0,1] neg_lo:[1,0,0] neg_hi:[1,0,0]
	v_pk_fma_f32 v[92:93], v[86:87], v[58:59], v[62:63] op_sel_hi:[1,0,1] neg_lo:[1,0,0] neg_hi:[1,0,0]
	s_waitcnt lgkmcnt(6)
	ds_read_b128 v[144:147], v49 offset:29440
	ds_read_b32 v160, v50 offset:29696
	ds_read_b128 v[152:155], v49 offset:30208
	ds_read_b128 v[148:151], v49 offset:29952
	ds_read_b128 v[156:159], v49 offset:30464
	ds_read_b128 v[140:143], v49 offset:29184
	v_pk_mul_f32 v[56:57], v[90:91], v[100:101]
	v_pk_mul_f32 v[64:65], v[70:71], v[92:93]
	v_pk_fma_f32 v[56:57], v[92:93], v[102:103], v[56:57]
	v_pk_fma_f32 v[64:65], v[68:69], v[90:91], v[64:65]
	v_add_f32_e32 v58, v56, v57
	v_add_f32_e32 v66, v64, v65
	v_pk_mul_f32 v[60:61], v[116:117], v[108:109] op_sel_hi:[0,1]
	v_add_f32_dpp v58, v58, v58 quad_perm:[1,0,3,2] row_mask:0xf bank_mask:0xf bound_ctrl:1
	v_add_f32_dpp v66, v66, v66 quad_perm:[1,0,3,2] row_mask:0xf bank_mask:0xf bound_ctrl:1
	v_pk_fma_f32 v[60:61], v[90:91], v[104:105], v[60:61]
	v_add_f32_dpp v58, v58, v58 quad_perm:[2,3,0,1] row_mask:0xf bank_mask:0xf bound_ctrl:1
	v_add_f32_dpp v66, v66, v66 quad_perm:[2,3,0,1] row_mask:0xf bank_mask:0xf bound_ctrl:1
	v_pk_mul_f32 v[62:63], v[116:117], v[110:111] op_sel_hi:[0,1]
	v_add_f32_dpp v58, v58, v58 row_half_mirror row_mask:0xf bank_mask:0xf bound_ctrl:1
	v_add_f32_dpp v66, v66, v66 row_half_mirror row_mask:0xf bank_mask:0xf bound_ctrl:1
	v_pk_fma_f32 v[62:63], v[92:93], v[106:107], v[62:63]
	v_add_f32_dpp v58, v58, v58 row_mirror row_mask:0xf bank_mask:0xf bound_ctrl:1
	v_add_f32_dpp v66, v66, v66 row_mirror row_mask:0xf bank_mask:0xf bound_ctrl:1
	v_pk_fma_f32 v[90:91], v[112:113], v[58:59], v[60:61] op_sel_hi:[1,0,1] neg_lo:[1,0,0] neg_hi:[1,0,0]
	v_pk_fma_f32 v[92:93], v[114:115], v[58:59], v[62:63] op_sel_hi:[1,0,1] neg_lo:[1,0,0] neg_hi:[1,0,0]
	v_cndmask_b32_e64 v67, 0, v66, s[38:39]
	s_waitcnt lgkmcnt(6)
	ds_read_b128 v[72:75], v49 offset:30976
	ds_read_b32 v88, v50 offset:31232
	ds_read_b128 v[80:83], v49 offset:31744
	ds_read_b128 v[76:79], v49 offset:31488
	ds_read_b128 v[84:87], v49 offset:32000
	ds_read_b128 v[68:71], v49 offset:30720
	v_pk_mul_f32 v[56:57], v[90:91], v[122:123]
	v_pk_mul_f32 v[64:65], v[98:99], v[92:93]
	v_pk_fma_f32 v[56:57], v[92:93], v[124:125], v[56:57]
	v_pk_fma_f32 v[64:65], v[96:97], v[90:91], v[64:65]
	v_add_f32_e32 v58, v56, v57
	v_add_f32_e32 v66, v64, v65
	v_pk_mul_f32 v[60:61], v[138:139], v[130:131] op_sel_hi:[0,1]
	v_add_f32_dpp v58, v58, v58 quad_perm:[1,0,3,2] row_mask:0xf bank_mask:0xf bound_ctrl:1
	v_add_f32_dpp v66, v66, v66 quad_perm:[1,0,3,2] row_mask:0xf bank_mask:0xf bound_ctrl:1
	v_pk_fma_f32 v[60:61], v[90:91], v[126:127], v[60:61]
	v_add_f32_dpp v58, v58, v58 quad_perm:[2,3,0,1] row_mask:0xf bank_mask:0xf bound_ctrl:1
	v_add_f32_dpp v66, v66, v66 quad_perm:[2,3,0,1] row_mask:0xf bank_mask:0xf bound_ctrl:1
	v_pk_mul_f32 v[62:63], v[138:139], v[132:133] op_sel_hi:[0,1]
	v_add_f32_dpp v58, v58, v58 row_half_mirror row_mask:0xf bank_mask:0xf bound_ctrl:1
	v_add_f32_dpp v66, v66, v66 row_half_mirror row_mask:0xf bank_mask:0xf bound_ctrl:1
	v_pk_fma_f32 v[62:63], v[92:93], v[128:129], v[62:63]
	v_add_f32_dpp v58, v58, v58 row_mirror row_mask:0xf bank_mask:0xf bound_ctrl:1
	v_add_f32_dpp v66, v66, v66 row_mirror row_mask:0xf bank_mask:0xf bound_ctrl:1
	v_pk_fma_f32 v[90:91], v[134:135], v[58:59], v[60:61] op_sel_hi:[1,0,1] neg_lo:[1,0,0] neg_hi:[1,0,0]
	v_pk_fma_f32 v[92:93], v[136:137], v[58:59], v[62:63] op_sel_hi:[1,0,1] neg_lo:[1,0,0] neg_hi:[1,0,0]
	v_cndmask_b32_e64 v67, v67, v66, s[40:41]
	s_waitcnt lgkmcnt(6)
; DI void scan_item(const Params& p, int item, char* smem) {
;     ...
;     for (int st = 0; st < 16; st++) {
;       StepIn nxt = cur;
;       if (st + 1 < 16) nxt = ldstep(base + (st + 1) * 6 * 64);
;       __builtin_amdgcn_sched_barrier(0);
;       f32x2 ra = {cur.r.x, cur.r.y}, rb = {cur.r.z, cur.r.w}, ka = {cur.k.x, cur.k.y}, kb = {cur.k.z, cur.k.w};
;       f32x2 wa = {cur.w.x, cur.w.y}, wb = {cur.w.z, cur.w.w}, da = {cur.d.x, cur.d.y}, db = {cur.d.z, cur.d.w};
;       f32x2 ba = {cur.b.x, cur.b.y}, bb2 = {cur.b.z, cur.b.w};
;       f32x2 pp = Sa * ka + Sb * kb;
;       float sa = allreduce16(pp.x + pp.y);
;       f32x2 vv2 = {cur.v, cur.v};
;       f32x2 sa2 = {sa, sa};
;       Sa = (Sa * wa + vv2 * da) - sa2 * ba;
;       Sb = (Sb * wb + vv2 * db) - sa2 * bb2;
;       f32x2 yy = Sa * ra + Sb * rb;
;       float y = allreduce16(yy.x + yy.y);
;       ykeep = (l16 == st) ? y : ykeep;
;       cur = nxt;
	ds_read_b128 v[100:103], v49 offset:32512
	ds_read_b32 v116, v50 offset:32768
	ds_read_b128 v[108:111], v49 offset:33280
	ds_read_b128 v[104:107], v49 offset:33024
	ds_read_b128 v[112:115], v49 offset:33536
	ds_read_b128 v[96:99], v49 offset:32256
	v_pk_mul_f32 v[56:57], v[90:91], v[144:145]
	v_pk_mul_f32 v[64:65], v[120:121], v[92:93]
	v_pk_fma_f32 v[56:57], v[92:93], v[146:147], v[56:57]
	v_pk_fma_f32 v[64:65], v[118:119], v[90:91], v[64:65]
	v_add_f32_e32 v58, v56, v57
	v_add_f32_e32 v66, v64, v65
	v_pk_mul_f32 v[60:61], v[160:161], v[152:153] op_sel_hi:[0,1]
	v_add_f32_dpp v58, v58, v58 quad_perm:[1,0,3,2] row_mask:0xf bank_mask:0xf bound_ctrl:1
	v_add_f32_dpp v66, v66, v66 quad_perm:[1,0,3,2] row_mask:0xf bank_mask:0xf bound_ctrl:1
	v_pk_fma_f32 v[60:61], v[90:91], v[148:149], v[60:61]
	v_add_f32_dpp v58, v58, v58 quad_perm:[2,3,0,1] row_mask:0xf bank_mask:0xf bound_ctrl:1
	v_add_f32_dpp v66, v66, v66 quad_perm:[2,3,0,1] row_mask:0xf bank_mask:0xf bound_ctrl:1
	v_pk_mul_f32 v[62:63], v[160:161], v[154:155] op_sel_hi:[0,1]
	v_add_f32_dpp v58, v58, v58 row_half_mirror row_mask:0xf bank_mask:0xf bound_ctrl:1
	v_add_f32_dpp v66, v66, v66 row_half_mirror row_mask:0xf bank_mask:0xf bound_ctrl:1
	v_pk_fma_f32 v[62:63], v[92:93], v[150:151], v[62:63]
	v_add_f32_dpp v58, v58, v58 row_mirror row_mask:0xf bank_mask:0xf bound_ctrl:1
	v_add_f32_dpp v66, v66, v66 row_mirror row_mask:0xf bank_mask:0xf bound_ctrl:1
	v_pk_fma_f32 v[90:91], v[156:157], v[58:59], v[60:61] op_sel_hi:[1,0,1] neg_lo:[1,0,0] neg_hi:[1,0,0]
	v_pk_fma_f32 v[92:93], v[158:159], v[58:59], v[62:63] op_sel_hi:[1,0,1] neg_lo:[1,0,0] neg_hi:[1,0,0]
	v_cndmask_b32_e64 v67, v67, v66, s[42:43]
	s_waitcnt lgkmcnt(6)
	ds_read_b128 v[122:125], v49 offset:34048
	ds_read_b32 v138, v50 offset:34304
	ds_read_b128 v[130:133], v49 offset:34816
	ds_read_b128 v[126:129], v49 offset:34560
	ds_read_b128 v[134:137], v49 offset:35072
	ds_read_b128 v[118:121], v49 offset:33792
	v_pk_mul_f32 v[56:57], v[90:91], v[72:73]
	v_pk_mul_f32 v[64:65], v[142:143], v[92:93]
	v_pk_fma_f32 v[56:57], v[92:93], v[74:75], v[56:57]
	v_pk_fma_f32 v[64:65], v[140:141], v[90:91], v[64:65]
	v_add_f32_e32 v58, v56, v57
	v_add_f32_e32 v66, v64, v65
	v_pk_mul_f32 v[60:61], v[88:89], v[80:81] op_sel_hi:[0,1]
	v_add_f32_dpp v58, v58, v58 quad_perm:[1,0,3,2] row_mask:0xf bank_mask:0xf bound_ctrl:1
	v_add_f32_dpp v66, v66, v66 quad_perm:[1,0,3,2] row_mask:0xf bank_mask:0xf bound_ctrl:1
	v_pk_fma_f32 v[60:61], v[90:91], v[76:77], v[60:61]
	v_add_f32_dpp v58, v58, v58 quad_perm:[2,3,0,1] row_mask:0xf bank_mask:0xf bound_ctrl:1
	v_add_f32_dpp v66, v66, v66 quad_perm:[2,3,0,1] row_mask:0xf bank_mask:0xf bound_ctrl:1
	v_pk_mul_f32 v[62:63], v[88:89], v[82:83] op_sel_hi:[0,1]
	v_add_f32_dpp v58, v58, v58 row_half_mirror row_mask:0xf bank_mask:0xf bound_ctrl:1
	v_add_f32_dpp v66, v66, v66 row_half_mirror row_mask:0xf bank_mask:0xf bound_ctrl:1
	v_pk_fma_f32 v[62:63], v[92:93], v[78:79], v[62:63]
	v_add_f32_dpp v58, v58, v58 row_mirror row_mask:0xf bank_mask:0xf bound_ctrl:1
	v_add_f32_dpp v66, v66, v66 row_mirror row_mask:0xf bank_mask:0xf bound_ctrl:1
	v_pk_fma_f32 v[90:91], v[84:85], v[58:59], v[60:61] op_sel_hi:[1,0,1] neg_lo:[1,0,0] neg_hi:[1,0,0]
	v_pk_fma_f32 v[92:93], v[86:87], v[58:59], v[62:63] op_sel_hi:[1,0,1] neg_lo:[1,0,0] neg_hi:[1,0,0]
	v_cndmask_b32_e64 v67, v67, v66, s[44:45]
	s_waitcnt lgkmcnt(6)
	ds_read_b128 v[144:147], v49 offset:35584
	ds_read_b32 v160, v50 offset:35840
	ds_read_b128 v[152:155], v49 offset:36352
	ds_read_b128 v[148:151], v49 offset:36096
	ds_read_b128 v[156:159], v49 offset:36608
	ds_read_b128 v[140:143], v49 offset:35328
	v_pk_mul_f32 v[56:57], v[90:91], v[100:101]
	v_pk_mul_f32 v[64:65], v[70:71], v[92:93]
	v_pk_fma_f32 v[56:57], v[92:93], v[102:103], v[56:57]
	v_pk_fma_f32 v[64:65], v[68:69], v[90:91], v[64:65]
	v_add_f32_e32 v58, v56, v57
	v_add_f32_e32 v66, v64, v65
	v_pk_mul_f32 v[60:61], v[116:117], v[108:109] op_sel_hi:[0,1]
	v_add_f32_dpp v58, v58, v58 quad_perm:[1,0,3,2] row_mask:0xf bank_mask:0xf bound_ctrl:1
	v_add_f32_dpp v66, v66, v66 quad_perm:[1,0,3,2] row_mask:0xf bank_mask:0xf bound_ctrl:1
	v_pk_fma_f32 v[60:61], v[90:91], v[104:105], v[60:61]
	v_add_f32_dpp v58, v58, v58 quad_perm:[2,3,0,1] row_mask:0xf bank_mask:0xf bound_ctrl:1
	v_add_f32_dpp v66, v66, v66 quad_perm:[2,3,0,1] row_mask:0xf bank_mask:0xf bound_ctrl:1
	v_pk_mul_f32 v[62:63], v[116:117], v[110:111] op_sel_hi:[0,1]
	v_add_f32_dpp v58, v58, v58 row_half_mirror row_mask:0xf bank_mask:0xf bound_ctrl:1
	v_add_f32_dpp v66, v66, v66 row_half_mirror row_mask:0xf bank_mask:0xf bound_ctrl:1
	v_pk_fma_f32 v[62:63], v[92:93], v[106:107], v[62:63]
	v_add_f32_dpp v58, v58, v58 row_mirror row_mask:0xf bank_mask:0xf bound_ctrl:1
	v_add_f32_dpp v66, v66, v66 row_mirror row_mask:0xf bank_mask:0xf bound_ctrl:1
	v_pk_fma_f32 v[90:91], v[112:113], v[58:59], v[60:61] op_sel_hi:[1,0,1] neg_lo:[1,0,0] neg_hi:[1,0,0]
	v_pk_fma_f32 v[92:93], v[114:115], v[58:59], v[62:63] op_sel_hi:[1,0,1] neg_lo:[1,0,0] neg_hi:[1,0,0]
	v_cndmask_b32_e64 v67, v67, v66, s[46:47]
	s_waitcnt lgkmcnt(6)
; DI void scan_item(const Params& p, int item, char* smem) {
;     ...
;     for (int st = 0; st < 16; st++) {
;       StepIn nxt = cur;
;       if (st + 1 < 16) nxt = ldstep(base + (st + 1) * 6 * 64);
;       __builtin_amdgcn_sched_barrier(0);
;       f32x2 ra = {cur.r.x, cur.r.y}, rb = {cur.r.z, cur.r.w}, ka = {cur.k.x, cur.k.y}, kb = {cur.k.z, cur.k.w};
;       f32x2 wa = {cur.w.x, cur.w.y}, wb = {cur.w.z, cur.w.w}, da = {cur.d.x, cur.d.y}, db = {cur.d.z, cur.d.w};
;       f32x2 ba = {cur.b.x, cur.b.y}, bb2 = {cur.b.z, cur.b.w};
;       f32x2 pp = Sa * ka + Sb * kb;
;       float sa = allreduce16(pp.x + pp.y);
;       f32x2 vv2 = {cur.v, cur.v};
;       f32x2 sa2 = {sa, sa};
;       Sa = (Sa * wa + vv2 * da) - sa2 * ba;
;       Sb = (Sb * wb + vv2 * db) - sa2 * bb2;
;       f32x2 yy = Sa * ra + Sb * rb;
;       float y = allreduce16(yy.x + yy.y);
;       ykeep = (l16 == st) ? y : ykeep;
;       cur = nxt;
	ds_read_b128 v[72:75], v49 offset:37120
	ds_read_b32 v88, v50 offset:37376
	ds_read_b128 v[80:83], v49 offset:37888
	ds_read_b128 v[76:79], v49 offset:37632
	ds_read_b128 v[84:87], v49 offset:38144
	ds_read_b128 v[68:71], v49 offset:36864
	v_pk_mul_f32 v[56:57], v[90:91], v[122:123]
	v_pk_mul_f32 v[64:65], v[98:99], v[92:93]
	v_pk_fma_f32 v[56:57], v[92:93], v[124:125], v[56:57]
	v_pk_fma_f32 v[64:65], v[96:97], v[90:91], v[64:65]
	v_add_f32_e32 v58, v56, v57
	v_add_f32_e32 v66, v64, v65
	v_pk_mul_f32 v[60:61], v[138:139], v[130:131] op_sel_hi:[0,1]
	v_add_f32_dpp v58, v58, v58 quad_perm:[1,0,3,2] row_mask:0xf bank_mask:0xf bound_ctrl:1
	v_add_f32_dpp v66, v66, v66 quad_perm:[1,0,3,2] row_mask:0xf bank_mask:0xf bound_ctrl:1
	v_pk_fma_f32 v[60:61], v[90:91], v[126:127], v[60:61]
	v_add_f32_dpp v58, v58, v58 quad_perm:[2,3,0,1] row_mask:0xf bank_mask:0xf bound_ctrl:1
	v_add_f32_dpp v66, v66, v66 quad_perm:[2,3,0,1] row_mask:0xf bank_mask:0xf bound_ctrl:1
	v_pk_mul_f32 v[62:63], v[138:139], v[132:133] op_sel_hi:[0,1]
	v_add_f32_dpp v58, v58, v58 row_half_mirror row_mask:0xf bank_mask:0xf bound_ctrl:1
	v_add_f32_dpp v66, v66, v66 row_half_mirror row_mask:0xf bank_mask:0xf bound_ctrl:1
	v_pk_fma_f32 v[62:63], v[92:93], v[128:129], v[62:63]
	v_add_f32_dpp v58, v58, v58 row_mirror row_mask:0xf bank_mask:0xf bound_ctrl:1
	v_add_f32_dpp v66, v66, v66 row_mirror row_mask:0xf bank_mask:0xf bound_ctrl:1
	v_pk_fma_f32 v[90:91], v[134:135], v[58:59], v[60:61] op_sel_hi:[1,0,1] neg_lo:[1,0,0] neg_hi:[1,0,0]
	v_pk_fma_f32 v[92:93], v[136:137], v[58:59], v[62:63] op_sel_hi:[1,0,1] neg_lo:[1,0,0] neg_hi:[1,0,0]
	v_cndmask_b32_e64 v67, v67, v66, s[48:49]
	s_waitcnt lgkmcnt(6)
	ds_read_b128 v[100:103], v49 offset:38656
	ds_read_b32 v116, v50 offset:38912
	ds_read_b128 v[108:111], v49 offset:39424
	ds_read_b128 v[104:107], v49 offset:39168
	ds_read_b128 v[112:115], v49 offset:39680
	ds_read_b128 v[96:99], v49 offset:38400
	v_pk_mul_f32 v[56:57], v[90:91], v[144:145]
	v_pk_mul_f32 v[64:65], v[120:121], v[92:93]
	v_pk_fma_f32 v[56:57], v[92:93], v[146:147], v[56:57]
	v_pk_fma_f32 v[64:65], v[118:119], v[90:91], v[64:65]
	v_add_f32_e32 v58, v56, v57
	v_add_f32_e32 v66, v64, v65
	v_pk_mul_f32 v[60:61], v[160:161], v[152:153] op_sel_hi:[0,1]
	v_add_f32_dpp v58, v58, v58 quad_perm:[1,0,3,2] row_mask:0xf bank_mask:0xf bound_ctrl:1
	v_add_f32_dpp v66, v66, v66 quad_perm:[1,0,3,2] row_mask:0xf bank_mask:0xf bound_ctrl:1
	v_pk_fma_f32 v[60:61], v[90:91], v[148:149], v[60:61]
	v_add_f32_dpp v58, v58, v58 quad_perm:[2,3,0,1] row_mask:0xf bank_mask:0xf bound_ctrl:1
	v_add_f32_dpp v66, v66, v66 quad_perm:[2,3,0,1] row_mask:0xf bank_mask:0xf bound_ctrl:1
	v_pk_mul_f32 v[62:63], v[160:161], v[154:155] op_sel_hi:[0,1]
	v_add_f32_dpp v58, v58, v58 row_half_mirror row_mask:0xf bank_mask:0xf bound_ctrl:1
	v_add_f32_dpp v66, v66, v66 row_half_mirror row_mask:0xf bank_mask:0xf bound_ctrl:1
	v_pk_fma_f32 v[62:63], v[92:93], v[150:151], v[62:63]
	v_add_f32_dpp v58, v58, v58 row_mirror row_mask:0xf bank_mask:0xf bound_ctrl:1
	v_add_f32_dpp v66, v66, v66 row_mirror row_mask:0xf bank_mask:0xf bound_ctrl:1
	v_pk_fma_f32 v[90:91], v[156:157], v[58:59], v[60:61] op_sel_hi:[1,0,1] neg_lo:[1,0,0] neg_hi:[1,0,0]
	v_pk_fma_f32 v[92:93], v[158:159], v[58:59], v[62:63] op_sel_hi:[1,0,1] neg_lo:[1,0,0] neg_hi:[1,0,0]
	v_cndmask_b32_e64 v67, v67, v66, s[50:51]
	s_waitcnt lgkmcnt(6)
	ds_read_b128 v[122:125], v49 offset:40192
	ds_read_b32 v138, v50 offset:40448
	ds_read_b128 v[130:133], v49 offset:40960
	ds_read_b128 v[126:129], v49 offset:40704
	ds_read_b128 v[134:137], v49 offset:41216
	ds_read_b128 v[118:121], v49 offset:39936
	v_pk_mul_f32 v[56:57], v[90:91], v[72:73]
	v_pk_mul_f32 v[64:65], v[142:143], v[92:93]
	v_pk_fma_f32 v[56:57], v[92:93], v[74:75], v[56:57]
	v_pk_fma_f32 v[64:65], v[140:141], v[90:91], v[64:65]
	v_add_f32_e32 v58, v56, v57
	v_add_f32_e32 v66, v64, v65
	v_pk_mul_f32 v[60:61], v[88:89], v[80:81] op_sel_hi:[0,1]
	v_add_f32_dpp v58, v58, v58 quad_perm:[1,0,3,2] row_mask:0xf bank_mask:0xf bound_ctrl:1
	v_add_f32_dpp v66, v66, v66 quad_perm:[1,0,3,2] row_mask:0xf bank_mask:0xf bound_ctrl:1
	v_pk_fma_f32 v[60:61], v[90:91], v[76:77], v[60:61]
	v_add_f32_dpp v58, v58, v58 quad_perm:[2,3,0,1] row_mask:0xf bank_mask:0xf bound_ctrl:1
	v_add_f32_dpp v66, v66, v66 quad_perm:[2,3,0,1] row_mask:0xf bank_mask:0xf bound_ctrl:1
	v_pk_mul_f32 v[62:63], v[88:89], v[82:83] op_sel_hi:[0,1]
	v_add_f32_dpp v58, v58, v58 row_half_mirror row_mask:0xf bank_mask:0xf bound_ctrl:1
	v_add_f32_dpp v66, v66, v66 row_half_mirror row_mask:0xf bank_mask:0xf bound_ctrl:1
	v_pk_fma_f32 v[62:63], v[92:93], v[78:79], v[62:63]
	v_add_f32_dpp v58, v58, v58 row_mirror row_mask:0xf bank_mask:0xf bound_ctrl:1
	v_add_f32_dpp v66, v66, v66 row_mirror row_mask:0xf bank_mask:0xf bound_ctrl:1
	v_pk_fma_f32 v[90:91], v[84:85], v[58:59], v[60:61] op_sel_hi:[1,0,1] neg_lo:[1,0,0] neg_hi:[1,0,0]
	v_pk_fma_f32 v[92:93], v[86:87], v[58:59], v[62:63] op_sel_hi:[1,0,1] neg_lo:[1,0,0] neg_hi:[1,0,0]
	v_cndmask_b32_e64 v67, v67, v66, s[52:53]
	s_waitcnt lgkmcnt(6)
; DI void scan_item(const Params& p, int item, char* smem) {
;     ...
;     for (int st = 0; st < 16; st++) {
;       StepIn nxt = cur;
;       if (st + 1 < 16) nxt = ldstep(base + (st + 1) * 6 * 64);
;       __builtin_amdgcn_sched_barrier(0);
;       f32x2 ra = {cur.r.x, cur.r.y}, rb = {cur.r.z, cur.r.w}, ka = {cur.k.x, cur.k.y}, kb = {cur.k.z, cur.k.w};
;       f32x2 wa = {cur.w.x, cur.w.y}, wb = {cur.w.z, cur.w.w}, da = {cur.d.x, cur.d.y}, db = {cur.d.z, cur.d.w};
;       f32x2 ba = {cur.b.x, cur.b.y}, bb2 = {cur.b.z, cur.b.w};
;       f32x2 pp = Sa * ka + Sb * kb;
;       float sa = allreduce16(pp.x + pp.y);
;       f32x2 vv2 = {cur.v, cur.v};
;       f32x2 sa2 = {sa, sa};
;       Sa = (Sa * wa + vv2 * da) - sa2 * ba;
;       Sb = (Sb * wb + vv2 * db) - sa2 * bb2;
;       f32x2 yy = Sa * ra + Sb * rb;
;       float y = allreduce16(yy.x + yy.y);
;       ykeep = (l16 == st) ? y : ykeep;
;       cur = nxt;
	ds_read_b128 v[144:147], v49 offset:41728
	ds_read_b32 v160, v50 offset:41984
	ds_read_b128 v[152:155], v49 offset:42496
	ds_read_b128 v[148:151], v49 offset:42240
	ds_read_b128 v[156:159], v49 offset:42752
	ds_read_b128 v[140:143], v49 offset:41472
	v_pk_mul_f32 v[56:57], v[90:91], v[100:101]
	v_pk_mul_f32 v[64:65], v[70:71], v[92:93]
	v_pk_fma_f32 v[56:57], v[92:93], v[102:103], v[56:57]
	v_pk_fma_f32 v[64:65], v[68:69], v[90:91], v[64:65]
	v_add_f32_e32 v58, v56, v57
	v_add_f32_e32 v66, v64, v65
	v_pk_mul_f32 v[60:61], v[116:117], v[108:109] op_sel_hi:[0,1]
	v_add_f32_dpp v58, v58, v58 quad_perm:[1,0,3,2] row_mask:0xf bank_mask:0xf bound_ctrl:1
	v_add_f32_dpp v66, v66, v66 quad_perm:[1,0,3,2] row_mask:0xf bank_mask:0xf bound_ctrl:1
	v_pk_fma_f32 v[60:61], v[90:91], v[104:105], v[60:61]
	v_add_f32_dpp v58, v58, v58 quad_perm:[2,3,0,1] row_mask:0xf bank_mask:0xf bound_ctrl:1
	v_add_f32_dpp v66, v66, v66 quad_perm:[2,3,0,1] row_mask:0xf bank_mask:0xf bound_ctrl:1
	v_pk_mul_f32 v[62:63], v[116:117], v[110:111] op_sel_hi:[0,1]
	v_add_f32_dpp v58, v58, v58 row_half_mirror row_mask:0xf bank_mask:0xf bound_ctrl:1
	v_add_f32_dpp v66, v66, v66 row_half_mirror row_mask:0xf bank_mask:0xf bound_ctrl:1
	v_pk_fma_f32 v[62:63], v[92:93], v[106:107], v[62:63]
	v_add_f32_dpp v58, v58, v58 row_mirror row_mask:0xf bank_mask:0xf bound_ctrl:1
	v_add_f32_dpp v66, v66, v66 row_mirror row_mask:0xf bank_mask:0xf bound_ctrl:1
	v_pk_fma_f32 v[90:91], v[112:113], v[58:59], v[60:61] op_sel_hi:[1,0,1] neg_lo:[1,0,0] neg_hi:[1,0,0]
	v_pk_fma_f32 v[92:93], v[114:115], v[58:59], v[62:63] op_sel_hi:[1,0,1] neg_lo:[1,0,0] neg_hi:[1,0,0]
	v_cndmask_b32_e64 v67, v67, v66, s[54:55]
	s_waitcnt lgkmcnt(6)
	ds_read_b128 v[72:75], v49 offset:43264
	ds_read_b32 v88, v50 offset:43520
	ds_read_b128 v[80:83], v49 offset:44032
	ds_read_b128 v[76:79], v49 offset:43776
	ds_read_b128 v[84:87], v49 offset:44288
	ds_read_b128 v[68:71], v49 offset:43008
	v_pk_mul_f32 v[56:57], v[90:91], v[122:123]
	v_pk_mul_f32 v[64:65], v[98:99], v[92:93]
	v_pk_fma_f32 v[56:57], v[92:93], v[124:125], v[56:57]
	v_pk_fma_f32 v[64:65], v[96:97], v[90:91], v[64:65]
	v_add_f32_e32 v58, v56, v57
	v_add_f32_e32 v66, v64, v65
	v_pk_mul_f32 v[60:61], v[138:139], v[130:131] op_sel_hi:[0,1]
	v_add_f32_dpp v58, v58, v58 quad_perm:[1,0,3,2] row_mask:0xf bank_mask:0xf bound_ctrl:1
	v_add_f32_dpp v66, v66, v66 quad_perm:[1,0,3,2] row_mask:0xf bank_mask:0xf bound_ctrl:1
	v_pk_fma_f32 v[60:61], v[90:91], v[126:127], v[60:61]
	v_add_f32_dpp v58, v58, v58 quad_perm:[2,3,0,1] row_mask:0xf bank_mask:0xf bound_ctrl:1
	v_add_f32_dpp v66, v66, v66 quad_perm:[2,3,0,1] row_mask:0xf bank_mask:0xf bound_ctrl:1
	v_pk_mul_f32 v[62:63], v[138:139], v[132:133] op_sel_hi:[0,1]
	v_add_f32_dpp v58, v58, v58 row_half_mirror row_mask:0xf bank_mask:0xf bound_ctrl:1
	v_add_f32_dpp v66, v66, v66 row_half_mirror row_mask:0xf bank_mask:0xf bound_ctrl:1
	v_pk_fma_f32 v[62:63], v[92:93], v[128:129], v[62:63]
	v_add_f32_dpp v58, v58, v58 row_mirror row_mask:0xf bank_mask:0xf bound_ctrl:1
	v_add_f32_dpp v66, v66, v66 row_mirror row_mask:0xf bank_mask:0xf bound_ctrl:1
	v_pk_fma_f32 v[90:91], v[134:135], v[58:59], v[60:61] op_sel_hi:[1,0,1] neg_lo:[1,0,0] neg_hi:[1,0,0]
	v_pk_fma_f32 v[92:93], v[136:137], v[58:59], v[62:63] op_sel_hi:[1,0,1] neg_lo:[1,0,0] neg_hi:[1,0,0]
	v_cndmask_b32_e64 v67, v67, v66, s[56:57]
	s_waitcnt lgkmcnt(6)
	ds_read_b128 v[100:103], v49 offset:44800
	ds_read_b32 v116, v50 offset:45056
	ds_read_b128 v[108:111], v49 offset:45568
	ds_read_b128 v[104:107], v49 offset:45312
	ds_read_b128 v[112:115], v49 offset:45824
	ds_read_b128 v[96:99], v49 offset:44544
	v_pk_mul_f32 v[56:57], v[90:91], v[144:145]
	v_pk_mul_f32 v[64:65], v[120:121], v[92:93]
	v_pk_fma_f32 v[56:57], v[92:93], v[146:147], v[56:57]
	v_pk_fma_f32 v[64:65], v[118:119], v[90:91], v[64:65]
	v_add_f32_e32 v58, v56, v57
	v_add_f32_e32 v66, v64, v65
	v_pk_mul_f32 v[60:61], v[160:161], v[152:153] op_sel_hi:[0,1]
	v_add_f32_dpp v58, v58, v58 quad_perm:[1,0,3,2] row_mask:0xf bank_mask:0xf bound_ctrl:1
	v_add_f32_dpp v66, v66, v66 quad_perm:[1,0,3,2] row_mask:0xf bank_mask:0xf bound_ctrl:1
	v_pk_fma_f32 v[60:61], v[90:91], v[148:149], v[60:61]
	v_add_f32_dpp v58, v58, v58 quad_perm:[2,3,0,1] row_mask:0xf bank_mask:0xf bound_ctrl:1
	v_add_f32_dpp v66, v66, v66 quad_perm:[2,3,0,1] row_mask:0xf bank_mask:0xf bound_ctrl:1
	v_pk_mul_f32 v[62:63], v[160:161], v[154:155] op_sel_hi:[0,1]
	v_add_f32_dpp v58, v58, v58 row_half_mirror row_mask:0xf bank_mask:0xf bound_ctrl:1
	v_add_f32_dpp v66, v66, v66 row_half_mirror row_mask:0xf bank_mask:0xf bound_ctrl:1
	v_pk_fma_f32 v[62:63], v[92:93], v[150:151], v[62:63]
	v_add_f32_dpp v58, v58, v58 row_mirror row_mask:0xf bank_mask:0xf bound_ctrl:1
	v_add_f32_dpp v66, v66, v66 row_mirror row_mask:0xf bank_mask:0xf bound_ctrl:1
	v_pk_fma_f32 v[90:91], v[156:157], v[58:59], v[60:61] op_sel_hi:[1,0,1] neg_lo:[1,0,0] neg_hi:[1,0,0]
	v_pk_fma_f32 v[92:93], v[158:159], v[58:59], v[62:63] op_sel_hi:[1,0,1] neg_lo:[1,0,0] neg_hi:[1,0,0]
	v_cndmask_b32_e64 v67, v67, v66, s[58:59]
	s_waitcnt lgkmcnt(6)
; DI void scan_item(const Params& p, int item, char* smem) {
;     ...
;     for (int st = 0; st < 16; st++) {
;       StepIn nxt = cur;
;       if (st + 1 < 16) nxt = ldstep(base + (st + 1) * 6 * 64);
;       __builtin_amdgcn_sched_barrier(0);
;       f32x2 ra = {cur.r.x, cur.r.y}, rb = {cur.r.z, cur.r.w}, ka = {cur.k.x, cur.k.y}, kb = {cur.k.z, cur.k.w};
;       f32x2 wa = {cur.w.x, cur.w.y}, wb = {cur.w.z, cur.w.w}, da = {cur.d.x, cur.d.y}, db = {cur.d.z, cur.d.w};
;       f32x2 ba = {cur.b.x, cur.b.y}, bb2 = {cur.b.z, cur.b.w};
;       f32x2 pp = Sa * ka + Sb * kb;
;       float sa = allreduce16(pp.x + pp.y);
;       f32x2 vv2 = {cur.v, cur.v};
;       f32x2 sa2 = {sa, sa};
;       Sa = (Sa * wa + vv2 * da) - sa2 * ba;
;       Sb = (Sb * wb + vv2 * db) - sa2 * bb2;
;       f32x2 yy = Sa * ra + Sb * rb;
;       float y = allreduce16(yy.x + yy.y);
;       ykeep = (l16 == st) ? y : ykeep;
;       cur = nxt;
	ds_read_b128 v[122:125], v49 offset:46336
	ds_read_b32 v138, v50 offset:46592
	ds_read_b128 v[130:133], v49 offset:47104
	ds_read_b128 v[126:129], v49 offset:46848
	ds_read_b128 v[134:137], v49 offset:47360
	ds_read_b128 v[118:121], v49 offset:46080
	v_pk_mul_f32 v[56:57], v[90:91], v[72:73]
	v_pk_mul_f32 v[64:65], v[142:143], v[92:93]
	v_pk_fma_f32 v[56:57], v[92:93], v[74:75], v[56:57]
	v_pk_fma_f32 v[64:65], v[140:141], v[90:91], v[64:65]
	v_add_f32_e32 v58, v56, v57
	v_add_f32_e32 v66, v64, v65
	v_pk_mul_f32 v[60:61], v[88:89], v[80:81] op_sel_hi:[0,1]
	v_add_f32_dpp v58, v58, v58 quad_perm:[1,0,3,2] row_mask:0xf bank_mask:0xf bound_ctrl:1
	v_add_f32_dpp v66, v66, v66 quad_perm:[1,0,3,2] row_mask:0xf bank_mask:0xf bound_ctrl:1
	v_pk_fma_f32 v[60:61], v[90:91], v[76:77], v[60:61]
	v_add_f32_dpp v58, v58, v58 quad_perm:[2,3,0,1] row_mask:0xf bank_mask:0xf bound_ctrl:1
	v_add_f32_dpp v66, v66, v66 quad_perm:[2,3,0,1] row_mask:0xf bank_mask:0xf bound_ctrl:1
	v_pk_mul_f32 v[62:63], v[88:89], v[82:83] op_sel_hi:[0,1]
	v_add_f32_dpp v58, v58, v58 row_half_mirror row_mask:0xf bank_mask:0xf bound_ctrl:1
	v_add_f32_dpp v66, v66, v66 row_half_mirror row_mask:0xf bank_mask:0xf bound_ctrl:1
	v_pk_fma_f32 v[62:63], v[92:93], v[78:79], v[62:63]
	v_add_f32_dpp v58, v58, v58 row_mirror row_mask:0xf bank_mask:0xf bound_ctrl:1
	v_add_f32_dpp v66, v66, v66 row_mirror row_mask:0xf bank_mask:0xf bound_ctrl:1
	v_pk_fma_f32 v[90:91], v[84:85], v[58:59], v[60:61] op_sel_hi:[1,0,1] neg_lo:[1,0,0] neg_hi:[1,0,0]
	v_pk_fma_f32 v[92:93], v[86:87], v[58:59], v[62:63] op_sel_hi:[1,0,1] neg_lo:[1,0,0] neg_hi:[1,0,0]
	v_cndmask_b32_e64 v67, v67, v66, s[60:61]
	s_waitcnt lgkmcnt(6)
	ds_read_b128 v[144:147], v49 offset:47872
	ds_read_b32 v160, v50 offset:48128
	ds_read_b128 v[152:155], v49 offset:48640
	ds_read_b128 v[148:151], v49 offset:48384
	ds_read_b128 v[156:159], v49 offset:48896
	ds_read_b128 v[140:143], v49 offset:47616
	v_pk_mul_f32 v[56:57], v[90:91], v[100:101]
	v_pk_mul_f32 v[64:65], v[70:71], v[92:93]
	v_pk_fma_f32 v[56:57], v[92:93], v[102:103], v[56:57]
	v_pk_fma_f32 v[64:65], v[68:69], v[90:91], v[64:65]
	v_add_f32_e32 v58, v56, v57
	v_add_f32_e32 v66, v64, v65
	v_pk_mul_f32 v[60:61], v[116:117], v[108:109] op_sel_hi:[0,1]
	v_add_f32_dpp v58, v58, v58 quad_perm:[1,0,3,2] row_mask:0xf bank_mask:0xf bound_ctrl:1
	v_add_f32_dpp v66, v66, v66 quad_perm:[1,0,3,2] row_mask:0xf bank_mask:0xf bound_ctrl:1
	v_pk_fma_f32 v[60:61], v[90:91], v[104:105], v[60:61]
	v_add_f32_dpp v58, v58, v58 quad_perm:[2,3,0,1] row_mask:0xf bank_mask:0xf bound_ctrl:1
	v_add_f32_dpp v66, v66, v66 quad_perm:[2,3,0,1] row_mask:0xf bank_mask:0xf bound_ctrl:1
	v_pk_mul_f32 v[62:63], v[116:117], v[110:111] op_sel_hi:[0,1]
	v_add_f32_dpp v58, v58, v58 row_half_mirror row_mask:0xf bank_mask:0xf bound_ctrl:1
	v_add_f32_dpp v66, v66, v66 row_half_mirror row_mask:0xf bank_mask:0xf bound_ctrl:1
	v_pk_fma_f32 v[62:63], v[92:93], v[106:107], v[62:63]
	v_add_f32_dpp v58, v58, v58 row_mirror row_mask:0xf bank_mask:0xf bound_ctrl:1
	v_add_f32_dpp v66, v66, v66 row_mirror row_mask:0xf bank_mask:0xf bound_ctrl:1
	v_pk_fma_f32 v[90:91], v[112:113], v[58:59], v[60:61] op_sel_hi:[1,0,1] neg_lo:[1,0,0] neg_hi:[1,0,0]
	v_pk_fma_f32 v[92:93], v[114:115], v[58:59], v[62:63] op_sel_hi:[1,0,1] neg_lo:[1,0,0] neg_hi:[1,0,0]
	v_cndmask_b32_e64 v67, v67, v66, s[62:63]
	s_waitcnt lgkmcnt(6)
	v_pk_mul_f32 v[56:57], v[90:91], v[122:123]
	v_pk_mul_f32 v[64:65], v[98:99], v[92:93]
	v_pk_fma_f32 v[56:57], v[92:93], v[124:125], v[56:57]
	v_pk_fma_f32 v[64:65], v[96:97], v[90:91], v[64:65]
	v_add_f32_e32 v58, v56, v57
	v_add_f32_e32 v66, v64, v65
	v_pk_mul_f32 v[60:61], v[138:139], v[130:131] op_sel_hi:[0,1]
	v_add_f32_dpp v58, v58, v58 quad_perm:[1,0,3,2] row_mask:0xf bank_mask:0xf bound_ctrl:1
	v_add_f32_dpp v66, v66, v66 quad_perm:[1,0,3,2] row_mask:0xf bank_mask:0xf bound_ctrl:1
	v_pk_fma_f32 v[60:61], v[90:91], v[126:127], v[60:61]
	v_add_f32_dpp v58, v58, v58 quad_perm:[2,3,0,1] row_mask:0xf bank_mask:0xf bound_ctrl:1
	v_add_f32_dpp v66, v66, v66 quad_perm:[2,3,0,1] row_mask:0xf bank_mask:0xf bound_ctrl:1
	v_pk_mul_f32 v[62:63], v[138:139], v[132:133] op_sel_hi:[0,1]
	v_add_f32_dpp v58, v58, v58 row_half_mirror row_mask:0xf bank_mask:0xf bound_ctrl:1
	v_add_f32_dpp v66, v66, v66 row_half_mirror row_mask:0xf bank_mask:0xf bound_ctrl:1
	v_pk_fma_f32 v[62:63], v[92:93], v[128:129], v[62:63]
	v_add_f32_dpp v58, v58, v58 row_mirror row_mask:0xf bank_mask:0xf bound_ctrl:1
	v_add_f32_dpp v66, v66, v66 row_mirror row_mask:0xf bank_mask:0xf bound_ctrl:1
	v_pk_fma_f32 v[90:91], v[134:135], v[58:59], v[60:61] op_sel_hi:[1,0,1] neg_lo:[1,0,0] neg_hi:[1,0,0]
	v_pk_fma_f32 v[92:93], v[136:137], v[58:59], v[62:63] op_sel_hi:[1,0,1] neg_lo:[1,0,0] neg_hi:[1,0,0]
	v_cndmask_b32_e64 v67, v67, v66, s[64:65]
	s_waitcnt lgkmcnt(0)
; DI void scan_item(const Params& p, int item, char* smem) {
;     ...
;   auto lstore = [&](int buf) {
; #pragma unroll
;     for (int i = 0; i < 3; i++) {
;       int id = tid + i * 256;
;       int st = id / 48, rem = id % 48, vec = rem >> 3, part = rem & 7;
;       h8 hv = __builtin_bit_cast(h8, rg_[i]);
;       f8 fv = __builtin_convertvector(hv, f8);
;       float* d = sIn + ((buf * 16 + st) * 6 + vec) * 64 + part * 8;
;       *(f32x4v*)d = f32x4v{fv[0], fv[1], fv[2], fv[3]};
;       *(f32x4v*)(d + 4) = f32x4v{fv[4], fv[5], fv[6], fv[7]};
;     }
;   };
;     ...
;     for (int st = 0; st < 16; st++) {
;       StepIn nxt = cur;
;       if (st + 1 < 16) nxt = ldstep(base + (st + 1) * 6 * 64);
;       __builtin_amdgcn_sched_barrier(0);
;       f32x2 ra = {cur.r.x, cur.r.y}, rb = {cur.r.z, cur.r.w}, ka = {cur.k.x, cur.k.y}, kb = {cur.k.z, cur.k.w};
;       f32x2 wa = {cur.w.x, cur.w.y}, wb = {cur.w.z, cur.w.w}, da = {cur.d.x, cur.d.y}, db = {cur.d.z, cur.d.w};
;       f32x2 ba = {cur.b.x, cur.b.y}, bb2 = {cur.b.z, cur.b.w};
;       f32x2 pp = Sa * ka + Sb * kb;
;       float sa = allreduce16(pp.x + pp.y);
;       f32x2 vv2 = {cur.v, cur.v};
;       f32x2 sa2 = {sa, sa};
;       Sa = (Sa * wa + vv2 * da) - sa2 * ba;
;       Sb = (Sb * wb + vv2 * db) - sa2 * bb2;
;       f32x2 yy = Sa * ra + Sb * rb;
;       float y = allreduce16(yy.x + yy.y);
;       ykeep = (l16 == st) ? y : ykeep;
;       cur = nxt;
;     }
;     { _Float16 yh = (_Float16)ykeep; yb[(long)tof(ci * 16 + l16) * 256 + rowl] = __builtin_bit_cast(u16, yh); }
;     if (ci + 1 < nch) lstore((ci + 1) & 1);
;     __syncthreads();
;   }
	v_pk_mul_f32 v[56:57], v[90:91], v[144:145]
	v_pk_mul_f32 v[64:65], v[120:121], v[92:93]
	v_pk_fma_f32 v[56:57], v[92:93], v[146:147], v[56:57]
	v_pk_fma_f32 v[64:65], v[118:119], v[90:91], v[64:65]
	v_add_f32_e32 v58, v56, v57
	v_add_f32_e32 v66, v64, v65
	v_pk_mul_f32 v[60:61], v[160:161], v[152:153] op_sel_hi:[0,1]
	v_add_f32_dpp v58, v58, v58 quad_perm:[1,0,3,2] row_mask:0xf bank_mask:0xf bound_ctrl:1
	v_add_f32_dpp v66, v66, v66 quad_perm:[1,0,3,2] row_mask:0xf bank_mask:0xf bound_ctrl:1
	v_pk_fma_f32 v[60:61], v[90:91], v[148:149], v[60:61]
	v_add_f32_dpp v58, v58, v58 quad_perm:[2,3,0,1] row_mask:0xf bank_mask:0xf bound_ctrl:1
	v_add_f32_dpp v66, v66, v66 quad_perm:[2,3,0,1] row_mask:0xf bank_mask:0xf bound_ctrl:1
	v_pk_mul_f32 v[62:63], v[160:161], v[154:155] op_sel_hi:[0,1]
	v_add_f32_dpp v58, v58, v58 row_half_mirror row_mask:0xf bank_mask:0xf bound_ctrl:1
	v_add_f32_dpp v66, v66, v66 row_half_mirror row_mask:0xf bank_mask:0xf bound_ctrl:1
	v_pk_fma_f32 v[62:63], v[92:93], v[150:151], v[62:63]
	v_add_f32_dpp v58, v58, v58 row_mirror row_mask:0xf bank_mask:0xf bound_ctrl:1
	v_add_f32_dpp v66, v66, v66 row_mirror row_mask:0xf bank_mask:0xf bound_ctrl:1
	v_pk_fma_f32 v[90:91], v[156:157], v[58:59], v[60:61] op_sel_hi:[1,0,1] neg_lo:[1,0,0] neg_hi:[1,0,0]
	v_pk_fma_f32 v[92:93], v[158:159], v[58:59], v[62:63] op_sel_hi:[1,0,1] neg_lo:[1,0,0] neg_hi:[1,0,0]
	v_cndmask_b32_e64 v67, v67, v66, s[66:67]
	s_nop 0
	v_pk_mul_f32 v[64:65], v[142:143], v[92:93]
	s_cmpk_gt_u32 s26, 0xff
	s_movk_i32 s12, 0x11ff
	s_cselect_b32 s12, s12, 0xff
	v_pk_fma_f32 v[64:65], v[140:141], v[90:91], v[64:65]
	s_sub_i32 s12, s12, s26
	v_add_u32_e32 v46, s26, v36
	v_add_f32_e32 v66, v64, v65
	v_sub_u32_e32 v47, s12, v36
	v_cndmask_b32_e64 v46, v47, v46, s[36:37]
	v_add_f32_dpp v66, v66, v66 quad_perm:[1,0,3,2] row_mask:0xf bank_mask:0xf bound_ctrl:1
	v_mov_b32_e32 v47, 0
	v_lshlrev_b64 v[46:47], 9, v[46:47]
	v_add_f32_dpp v66, v66, v66 quad_perm:[2,3,0,1] row_mask:0xf bank_mask:0xf bound_ctrl:1
	v_lshl_add_u64 v[46:47], v[30:31], 0, v[46:47]
	s_nop 0
	v_add_f32_dpp v66, v66, v66 row_half_mirror row_mask:0xf bank_mask:0xf bound_ctrl:1
	s_nop 1
	v_add_f32_dpp v66, v66, v66 row_mirror row_mask:0xf bank_mask:0xf bound_ctrl:1
	v_cndmask_b32_e64 v67, v67, v66, s[68:69]
	v_cvt_f16_f32_e32 v45, v67
	global_store_short v[46:47], v45, off
	s_waitcnt vmcnt(6)
	v_cvt_f32_f16_e32 v40, v162
	v_cvt_f32_f16_sdwa v41, v162 dst_sel:DWORD dst_unused:UNUSED_PAD src0_sel:WORD_1
	v_cvt_f32_f16_e32 v42, v163
	v_cvt_f32_f16_sdwa v43, v163 dst_sel:DWORD dst_unused:UNUSED_PAD src0_sel:WORD_1
	v_cvt_f32_f16_e32 v44, v164
	v_cvt_f32_f16_sdwa v45, v164 dst_sel:DWORD dst_unused:UNUSED_PAD src0_sel:WORD_1
	v_cvt_f32_f16_e32 v46, v165
	v_cvt_f32_f16_sdwa v47, v165 dst_sel:DWORD dst_unused:UNUSED_PAD src0_sel:WORD_1
	ds_write_b128 v32, v[40:43]
	ds_write_b128 v32, v[44:47] offset:16
	s_waitcnt vmcnt(5)
	v_cvt_f32_f16_e32 v40, v166
	v_cvt_f32_f16_sdwa v41, v166 dst_sel:DWORD dst_unused:UNUSED_PAD src0_sel:WORD_1
	v_cvt_f32_f16_e32 v42, v167
	v_cvt_f32_f16_sdwa v43, v167 dst_sel:DWORD dst_unused:UNUSED_PAD src0_sel:WORD_1
	v_cvt_f32_f16_e32 v44, v168
	v_cvt_f32_f16_sdwa v45, v168 dst_sel:DWORD dst_unused:UNUSED_PAD src0_sel:WORD_1
	v_cvt_f32_f16_e32 v46, v169
	v_cvt_f32_f16_sdwa v47, v169 dst_sel:DWORD dst_unused:UNUSED_PAD src0_sel:WORD_1
	ds_write_b128 v33, v[40:43]
	ds_write_b128 v33, v[44:47] offset:16
	s_waitcnt vmcnt(4)
	v_cvt_f32_f16_e32 v40, v170
	v_cvt_f32_f16_sdwa v41, v170 dst_sel:DWORD dst_unused:UNUSED_PAD src0_sel:WORD_1
	v_cvt_f32_f16_e32 v42, v171
	v_cvt_f32_f16_sdwa v43, v171 dst_sel:DWORD dst_unused:UNUSED_PAD src0_sel:WORD_1
	v_cvt_f32_f16_e32 v44, v172
	v_cvt_f32_f16_sdwa v45, v172 dst_sel:DWORD dst_unused:UNUSED_PAD src0_sel:WORD_1
	v_cvt_f32_f16_e32 v46, v173
	v_cvt_f32_f16_sdwa v47, v173 dst_sel:DWORD dst_unused:UNUSED_PAD src0_sel:WORD_1
	ds_write_b128 v34, v[40:43]
	ds_write_b128 v34, v[44:47] offset:16
	s_add_i32 s26, s26, 16
	s_waitcnt lgkmcnt(0)
	s_barrier
	s_cmpk_lg_i32 s26, 0x1100
	s_cbranch_scc1 .Lscan_loop
	s_waitcnt vmcnt(0)
	s_branch .LBB0_155
